# conv tile: main x-row loads (28 of 32 rows) issued together with the halo batch before its wait
# speedup vs baseline: 1.0031x; 1.0031x over previous
; __device__ __forceinline__ int opaque_tid() { int t = threadIdx.x; asm volatile("" : "+v"(t)); return t; }
; #define LAS __attribute__((address_space(3)))
; __device__ __forceinline__ void conv_tile(const Params& p, int l, int item, const bf16* PROJ, bf16* CV, LAS float* sl) {
;     const int tid = opaque_tid(), lane = tid & 63, wave = __builtin_amdgcn_readfirstlane(tid >> 6), c = tid;
;     const int m0 = item * 32, b = m0 / SEQ, s0 = m0 % SEQ;
;     LAS float* part = sl; LAS float* stat = sl + 512;
;     float u[62];
; #pragma unroll
;     for (int rr = 0; rr < 62; ++rr) { const int sq = s0 - 15 + rr; const bool ok = sq >= 0 && sq < SEQ; const bf16* pr = PROJ + (size_t)(b * SEQ + (ok ? sq : s0)) * NIN;
;         const float a = bf2f(pr[PB_A + c]), g = bf2f(pr[PB_G + c]); u[rr] = ok ? a / (1.0f + __expf(-g)) : 0.f; }
.LBB0_299:
	v_readlane_b32 s1, v252, 60
	v_readlane_b32 s12, v254, 62
	s_or_b32 s0, s0, s1
	v_readlane_b32 s13, v254, 63
	s_mov_b32 s9, s13
	s_lshl_b32 s8, s0, 5
	v_readlane_b32 s14, v255, 0
	v_readlane_b32 s15, v255, 1
	v_readlane_b32 s16, v255, 2
	v_readlane_b32 s17, v255, 3
	v_readlane_b32 s18, v255, 4
	v_readlane_b32 s19, v255, 5
	v_readlane_b32 s20, v255, 6
	v_readlane_b32 s21, v255, 7
	v_readlane_b32 s22, v255, 8
	v_readlane_b32 s23, v255, 9
	v_readlane_b32 s24, v255, 10
	v_readlane_b32 s25, v255, 11
	v_readlane_b32 s26, v255, 12
	v_readlane_b32 s27, v255, 13
	s_mov_b64 s[12:13], s[8:9]
	v_writelane_b32 v254, s12, 62
	v_mov_b32_e32 v2, v188
	s_and_b32 s1, s8, 0xfe0
	v_writelane_b32 v255, s14, 0
	v_writelane_b32 v255, s15, 1
	v_writelane_b32 v255, s16, 2
	v_writelane_b32 v255, s17, 3
	v_writelane_b32 v255, s18, 4
	v_writelane_b32 v255, s19, 5
	v_writelane_b32 v255, s20, 6
	v_writelane_b32 v255, s21, 7
	v_writelane_b32 v255, s22, 8
	v_writelane_b32 v255, s23, 9
	v_writelane_b32 v255, s24, 10
	v_writelane_b32 v255, s25, 11
	v_writelane_b32 v254, s13, 63
	v_writelane_b32 v255, s26, 12
	v_writelane_b32 v255, s27, 13
	v_readlane_b32 s12, v254, 6
	s_and_b32 s0, s8, 0x7ffff000
	s_add_i32 s8, s1, -15
	v_ashrrev_i32_e32 v3, 31, v2
	v_readlane_b32 s13, v254, 7
	v_mov_b32_e32 v26, 0
	s_cmpk_gt_u32 s8, 0xfff
	v_lshl_add_u64 v[4:5], v[2:3], 1, s[12:13]
	v_mov_b32_e32 v28, 0
	v_add_co_u32_e32 v164, vcc, 0xe00, v4
	s_nop 1
	v_addc_co_u32_e32 v165, vcc, 0, v5, vcc
	s_add_i32 s8, s1, -15
	s_cmpk_gt_u32 s8, 0xfff
	s_cselect_b32 s8, s1, s8
	s_or_b32 s8, s8, s0
	v_mad_u64_u32 v[6:7], s[8:9], s8, v195, v[164:165]
	global_load_ushort v208, v[6:7], off offset:512
	global_load_ushort v209, v[6:7], off offset:-512
	s_add_i32 s8, s1, -14
	s_cmpk_gt_u32 s8, 0xfff
	s_cselect_b32 s8, s1, s8
	s_or_b32 s8, s8, s0
	v_mad_u64_u32 v[6:7], s[8:9], s8, v195, v[164:165]
	global_load_ushort v210, v[6:7], off offset:512
	global_load_ushort v211, v[6:7], off offset:-512
	s_add_i32 s8, s1, -13
	s_cmpk_gt_u32 s8, 0xfff
	s_cselect_b32 s8, s1, s8
	s_or_b32 s8, s8, s0
	v_mad_u64_u32 v[6:7], s[8:9], s8, v195, v[164:165]
	global_load_ushort v212, v[6:7], off offset:512
	global_load_ushort v213, v[6:7], off offset:-512
	s_add_i32 s8, s1, -12
	s_cmpk_gt_u32 s8, 0xfff
	s_cselect_b32 s8, s1, s8
	s_or_b32 s8, s8, s0
	v_mad_u64_u32 v[6:7], s[8:9], s8, v195, v[164:165]
	global_load_ushort v214, v[6:7], off offset:512
	global_load_ushort v215, v[6:7], off offset:-512
	s_add_i32 s8, s1, -11
	s_cmpk_gt_u32 s8, 0xfff
	s_cselect_b32 s8, s1, s8
	s_or_b32 s8, s8, s0
	v_mad_u64_u32 v[6:7], s[8:9], s8, v195, v[164:165]
	global_load_ushort v216, v[6:7], off offset:512
	global_load_ushort v217, v[6:7], off offset:-512
	s_add_i32 s8, s1, -10
	s_cmpk_gt_u32 s8, 0xfff
	s_cselect_b32 s8, s1, s8
	s_or_b32 s8, s8, s0
	v_mad_u64_u32 v[6:7], s[8:9], s8, v195, v[164:165]
	global_load_ushort v218, v[6:7], off offset:512
	global_load_ushort v219, v[6:7], off offset:-512
	s_add_i32 s8, s1, -9
	s_cmpk_gt_u32 s8, 0xfff
	s_cselect_b32 s8, s1, s8
	s_or_b32 s8, s8, s0
	v_mad_u64_u32 v[6:7], s[8:9], s8, v195, v[164:165]
	global_load_ushort v220, v[6:7], off offset:512
	global_load_ushort v221, v[6:7], off offset:-512
	s_add_i32 s8, s1, -8
	s_cmpk_gt_u32 s8, 0xfff
	s_cselect_b32 s8, s1, s8
	s_or_b32 s8, s8, s0
	v_mad_u64_u32 v[6:7], s[8:9], s8, v195, v[164:165]
	global_load_ushort v222, v[6:7], off offset:512
	global_load_ushort v223, v[6:7], off offset:-512
	s_add_i32 s8, s1, -7
	s_cmpk_gt_u32 s8, 0xfff
	s_cselect_b32 s8, s1, s8
	s_or_b32 s8, s8, s0
	v_mad_u64_u32 v[6:7], s[8:9], s8, v195, v[164:165]
	global_load_ushort v224, v[6:7], off offset:512
	global_load_ushort v225, v[6:7], off offset:-512
	s_add_i32 s8, s1, -6
	s_cmpk_gt_u32 s8, 0xfff
	s_cselect_b32 s8, s1, s8
	s_or_b32 s8, s8, s0
	v_mad_u64_u32 v[6:7], s[8:9], s8, v195, v[164:165]
	global_load_ushort v226, v[6:7], off offset:512
	global_load_ushort v227, v[6:7], off offset:-512
	s_add_i32 s8, s1, -5
	s_cmpk_gt_u32 s8, 0xfff
	s_cselect_b32 s8, s1, s8
	s_or_b32 s8, s8, s0
	v_mad_u64_u32 v[6:7], s[8:9], s8, v195, v[164:165]
	global_load_ushort v228, v[6:7], off offset:512
	global_load_ushort v229, v[6:7], off offset:-512
	s_add_i32 s8, s1, -4
	s_cmpk_gt_u32 s8, 0xfff
	s_cselect_b32 s8, s1, s8
	s_or_b32 s8, s8, s0
	v_mad_u64_u32 v[6:7], s[8:9], s8, v195, v[164:165]
	global_load_ushort v230, v[6:7], off offset:512
	global_load_ushort v231, v[6:7], off offset:-512
	s_add_i32 s8, s1, -3
	s_cmpk_gt_u32 s8, 0xfff
	s_cselect_b32 s8, s1, s8
	s_or_b32 s8, s8, s0
	v_mad_u64_u32 v[6:7], s[8:9], s8, v195, v[164:165]
	global_load_ushort v232, v[6:7], off offset:512
	global_load_ushort v233, v[6:7], off offset:-512
	s_add_i32 s8, s1, -2
	s_cmpk_gt_u32 s8, 0xfff
	s_cselect_b32 s8, s1, s8
	s_or_b32 s8, s8, s0
	v_mad_u64_u32 v[6:7], s[8:9], s8, v195, v[164:165]
	global_load_ushort v234, v[6:7], off offset:512
	global_load_ushort v235, v[6:7], off offset:-512
	s_add_i32 s8, s1, -1
	s_cmpk_gt_u32 s8, 0xfff
	s_cselect_b32 s8, s1, s8
	s_or_b32 s8, s8, s0
	v_mad_u64_u32 v[6:7], s[8:9], s8, v195, v[164:165]
	global_load_ushort v236, v[6:7], off offset:512
	global_load_ushort v237, v[6:7], off offset:-512
	s_add_i32 s8, s1, 32
	s_cmpk_gt_u32 s8, 0xfff
	s_cselect_b32 s8, s1, s8
	s_or_b32 s8, s8, s0
	v_mad_u64_u32 v[6:7], s[8:9], s8, v195, v[164:165]
	global_load_ushort v238, v[6:7], off offset:512
	global_load_ushort v239, v[6:7], off offset:-512
	s_add_i32 s8, s1, 33
	s_cmpk_gt_u32 s8, 0xfff
	s_cselect_b32 s8, s1, s8
	s_or_b32 s8, s8, s0
	v_mad_u64_u32 v[6:7], s[8:9], s8, v195, v[164:165]
	global_load_ushort v240, v[6:7], off offset:512
	global_load_ushort v241, v[6:7], off offset:-512
; __device__ __forceinline__ void conv_tile(const Params& p, int l, int item, const bf16* PROJ, bf16* CV, LAS float* sl) {
;     ...
; #pragma unroll
;     for (int rr = 0; rr < 62; ++rr) { const int sq = s0 - 15 + rr; const bool ok = sq >= 0 && sq < SEQ; const bf16* pr = PROJ + (size_t)(b * SEQ + (ok ? sq : s0)) * NIN;
;         const float a = bf2f(pr[PB_A + c]), g = bf2f(pr[PB_G + c]); u[rr] = ok ? a / (1.0f + __expf(-g)) : 0.f; }
	s_add_i32 s8, s1, 34
	s_cmpk_gt_u32 s8, 0xfff
	s_cselect_b32 s8, s1, s8
	s_or_b32 s8, s8, s0
	v_mad_u64_u32 v[6:7], s[8:9], s8, v195, v[164:165]
	global_load_ushort v242, v[6:7], off offset:512
	global_load_ushort v243, v[6:7], off offset:-512
	s_add_i32 s8, s1, 35
	s_cmpk_gt_u32 s8, 0xfff
	s_cselect_b32 s8, s1, s8
	s_or_b32 s8, s8, s0
	v_mad_u64_u32 v[6:7], s[8:9], s8, v195, v[164:165]
	global_load_ushort v244, v[6:7], off offset:512
	global_load_ushort v245, v[6:7], off offset:-512
	s_add_i32 s8, s1, 36
	s_cmpk_gt_u32 s8, 0xfff
	s_cselect_b32 s8, s1, s8
	s_or_b32 s8, s8, s0
	v_mad_u64_u32 v[6:7], s[8:9], s8, v195, v[164:165]
	global_load_ushort v246, v[6:7], off offset:512
	global_load_ushort v247, v[6:7], off offset:-512
	s_add_i32 s8, s1, 37
	s_cmpk_gt_u32 s8, 0xfff
	s_cselect_b32 s8, s1, s8
	s_or_b32 s8, s8, s0
	v_mad_u64_u32 v[6:7], s[8:9], s8, v195, v[164:165]
	global_load_ushort v248, v[6:7], off offset:512
	global_load_ushort v249, v[6:7], off offset:-512
	s_add_i32 s8, s1, 38
	s_cmpk_gt_u32 s8, 0xfff
	s_cselect_b32 s8, s1, s8
	s_or_b32 s8, s8, s0
	v_mad_u64_u32 v[6:7], s[8:9], s8, v195, v[164:165]
	global_load_ushort v141, v[6:7], off offset:512
	global_load_ushort v142, v[6:7], off offset:-512
	s_add_i32 s8, s1, 39
	s_cmpk_gt_u32 s8, 0xfff
	s_cselect_b32 s8, s1, s8
	s_or_b32 s8, s8, s0
	v_mad_u64_u32 v[6:7], s[8:9], s8, v195, v[164:165]
	global_load_ushort v143, v[6:7], off offset:512
	global_load_ushort v144, v[6:7], off offset:-512
	s_add_i32 s8, s1, 40
	s_cmpk_gt_u32 s8, 0xfff
	s_cselect_b32 s8, s1, s8
	s_or_b32 s8, s8, s0
	v_mad_u64_u32 v[6:7], s[8:9], s8, v195, v[164:165]
	global_load_ushort v145, v[6:7], off offset:512
	global_load_ushort v146, v[6:7], off offset:-512
	s_add_i32 s8, s1, 41
	s_cmpk_gt_u32 s8, 0xfff
	s_cselect_b32 s8, s1, s8
	s_or_b32 s8, s8, s0
	v_mad_u64_u32 v[6:7], s[8:9], s8, v195, v[164:165]
	global_load_ushort v147, v[6:7], off offset:512
	global_load_ushort v148, v[6:7], off offset:-512
	s_add_i32 s8, s1, 42
	s_cmpk_gt_u32 s8, 0xfff
	s_cselect_b32 s8, s1, s8
	s_or_b32 s8, s8, s0
	v_mad_u64_u32 v[6:7], s[8:9], s8, v195, v[164:165]
	global_load_ushort v149, v[6:7], off offset:512
	global_load_ushort v150, v[6:7], off offset:-512
	s_add_i32 s8, s1, 43
	s_cmpk_gt_u32 s8, 0xfff
	s_cselect_b32 s8, s1, s8
	s_or_b32 s8, s8, s0
	v_mad_u64_u32 v[6:7], s[8:9], s8, v195, v[164:165]
	global_load_ushort v151, v[6:7], off offset:512
	global_load_ushort v152, v[6:7], off offset:-512
	s_add_i32 s8, s1, 44
	s_cmpk_gt_u32 s8, 0xfff
	s_cselect_b32 s8, s1, s8
	s_or_b32 s8, s8, s0
	v_mad_u64_u32 v[6:7], s[8:9], s8, v195, v[164:165]
	global_load_ushort v153, v[6:7], off offset:512
	global_load_ushort v156, v[6:7], off offset:-512
	s_add_i32 s8, s1, 45
	s_cmpk_gt_u32 s8, 0xfff
	s_cselect_b32 s8, s1, s8
	s_or_b32 s8, s8, s0
	v_mad_u64_u32 v[6:7], s[8:9], s8, v195, v[164:165]
	global_load_ushort v157, v[6:7], off offset:512
	global_load_ushort v158, v[6:7], off offset:-512
	s_add_i32 s8, s1, 46
	s_cmpk_gt_u32 s8, 0xfff
	s_cselect_b32 s8, s1, s8
	s_or_b32 s8, s8, s0
	v_mad_u64_u32 v[6:7], s[8:9], s8, v195, v[164:165]
	global_load_ushort v159, v[6:7], off offset:512
	global_load_ushort v160, v[6:7], off offset:-512
	v_readlane_b32 s80, v254, 62
	s_or_b32 s76, s80, 1
	s_or_b32 s74, s80, 2
	v_mad_u64_u32 v[8:9], s[8:9], s80, v195, v[4:5]
	v_add_co_u32_e32 v30, vcc, 0x1000, v8
	s_or_b32 s72, s80, 3
	s_nop 0
	v_addc_co_u32_e32 v31, vcc, 0, v9, vcc
	global_load_ushort v102, v[30:31], off
	global_load_ushort v101, v[8:9], off offset:3072
	v_mad_u64_u32 v[8:9], s[8:9], s76, v195, v[4:5]
	v_add_co_u32_e32 v30, vcc, 0x1000, v8
	s_or_b32 s70, s80, 4
	s_nop 0
	v_addc_co_u32_e32 v31, vcc, 0, v9, vcc
	global_load_ushort v100, v[30:31], off
	global_load_ushort v99, v[8:9], off offset:3072
	s_or_b32 s68, s80, 5
	v_mad_u64_u32 v[8:9], s[8:9], s72, v195, v[4:5]
	v_add_co_u32_e32 v32, vcc, 0x1000, v8
	s_or_b32 s66, s80, 6
	s_nop 0
	v_addc_co_u32_e32 v33, vcc, 0, v9, vcc
	global_load_ushort v98, v[32:33], off
	global_load_ushort v96, v[8:9], off offset:3072
	v_mad_u64_u32 v[8:9], s[8:9], s70, v195, v[4:5]
	v_add_co_u32_e32 v32, vcc, 0x1000, v8
	s_or_b32 s64, s80, 7
	s_nop 0
	v_addc_co_u32_e32 v33, vcc, 0, v9, vcc
	global_load_ushort v95, v[32:33], off
	global_load_ushort v94, v[8:9], off offset:3072
	v_mad_u64_u32 v[8:9], s[8:9], s68, v195, v[4:5]
	v_add_co_u32_e32 v32, vcc, 0x1000, v8
	s_or_b32 s62, s80, 8
	s_nop 0
	v_addc_co_u32_e32 v33, vcc, 0, v9, vcc
	global_load_ushort v93, v[32:33], off
	global_load_ushort v91, v[8:9], off offset:3072
	v_mad_u64_u32 v[8:9], s[8:9], s66, v195, v[4:5]
	v_add_co_u32_e32 v32, vcc, 0x1000, v8
	s_or_b32 s60, s80, 9
	s_nop 0
	v_addc_co_u32_e32 v33, vcc, 0, v9, vcc
	global_load_ushort v90, v[32:33], off
	global_load_ushort v81, v[8:9], off offset:3072
	v_mad_u64_u32 v[8:9], s[8:9], s64, v195, v[4:5]
	v_add_co_u32_e32 v32, vcc, 0x1000, v8
	s_or_b32 s58, s80, 10
	s_nop 0
	v_addc_co_u32_e32 v33, vcc, 0, v9, vcc
	global_load_ushort v92, v[32:33], off
	global_load_ushort v89, v[8:9], off offset:3072
	v_mad_u64_u32 v[8:9], s[8:9], s62, v195, v[4:5]
	v_add_co_u32_e32 v32, vcc, 0x1000, v8
	s_or_b32 s56, s80, 11
	s_nop 0
	v_addc_co_u32_e32 v33, vcc, 0, v9, vcc
	global_load_ushort v88, v[32:33], off
	global_load_ushort v77, v[8:9], off offset:3072
	v_mad_u64_u32 v[8:9], s[8:9], s60, v195, v[4:5]
	v_add_co_u32_e32 v32, vcc, 0x1000, v8
	s_or_b32 s54, s80, 12
	s_nop 0
	v_addc_co_u32_e32 v33, vcc, 0, v9, vcc
; __device__ __forceinline__ void conv_tile(const Params& p, int l, int item, const bf16* PROJ, bf16* CV, LAS float* sl) {
;     ...
; #pragma unroll
;     for (int rr = 0; rr < 62; ++rr) { const int sq = s0 - 15 + rr; const bool ok = sq >= 0 && sq < SEQ; const bf16* pr = PROJ + (size_t)(b * SEQ + (ok ? sq : s0)) * NIN;
;         const float a = bf2f(pr[PB_A + c]), g = bf2f(pr[PB_G + c]); u[rr] = ok ? a / (1.0f + __expf(-g)) : 0.f; }
	global_load_ushort v87, v[32:33], off
	global_load_ushort v76, v[8:9], off offset:3072
	v_mad_u64_u32 v[8:9], s[8:9], s58, v195, v[4:5]
	v_add_co_u32_e32 v32, vcc, 0x1000, v8
	s_or_b32 s52, s80, 13
	s_nop 0
	v_addc_co_u32_e32 v33, vcc, 0, v9, vcc
	global_load_ushort v74, v[32:33], off
	global_load_ushort v71, v[8:9], off offset:3072
	v_mad_u64_u32 v[8:9], s[8:9], s56, v195, v[4:5]
	v_add_co_u32_e32 v32, vcc, 0x1000, v8
	s_or_b32 s50, s80, 14
	s_nop 0
	v_addc_co_u32_e32 v33, vcc, 0, v9, vcc
	global_load_ushort v86, v[32:33], off
	global_load_ushort v85, v[8:9], off offset:3072
	v_mad_u64_u32 v[8:9], s[8:9], s54, v195, v[4:5]
	v_add_co_u32_e32 v32, vcc, 0x1000, v8
	s_or_b32 s48, s80, 15
	s_nop 0
	v_addc_co_u32_e32 v33, vcc, 0, v9, vcc
	global_load_ushort v84, v[32:33], off
	global_load_ushort v69, v[8:9], off offset:3072
	v_mad_u64_u32 v[8:9], s[8:9], s52, v195, v[4:5]
	v_add_co_u32_e32 v32, vcc, 0x1000, v8
	s_or_b32 s46, s80, 16
	s_nop 0
	v_addc_co_u32_e32 v33, vcc, 0, v9, vcc
	global_load_ushort v83, v[32:33], off
	global_load_ushort v66, v[8:9], off offset:3072
	v_mad_u64_u32 v[8:9], s[8:9], s50, v195, v[4:5]
	v_add_co_u32_e32 v32, vcc, 0x1000, v8
	s_or_b32 s42, s80, 17
	s_nop 0
	v_addc_co_u32_e32 v33, vcc, 0, v9, vcc
	global_load_ushort v63, v[32:33], off
	global_load_ushort v61, v[8:9], off offset:3072
	v_mad_u64_u32 v[8:9], s[8:9], s48, v195, v[4:5]
	v_add_co_u32_e32 v32, vcc, 0x1000, v8
	s_or_b32 s40, s80, 18
	s_nop 0
	v_addc_co_u32_e32 v33, vcc, 0, v9, vcc
	global_load_ushort v82, v[32:33], off
	global_load_ushort v80, v[8:9], off offset:3072
	v_mad_u64_u32 v[8:9], s[8:9], s46, v195, v[4:5]
	v_add_co_u32_e32 v32, vcc, 0x1000, v8
	s_or_b32 s36, s80, 19
	s_nop 0
	v_addc_co_u32_e32 v33, vcc, 0, v9, vcc
	global_load_ushort v79, v[32:33], off
	global_load_ushort v58, v[8:9], off offset:3072
	v_mad_u64_u32 v[8:9], s[8:9], s42, v195, v[4:5]
	v_add_co_u32_e32 v32, vcc, 0x1000, v8
	s_or_b32 s34, s80, 20
	s_nop 0
	v_addc_co_u32_e32 v33, vcc, 0, v9, vcc
	global_load_ushort v78, v[32:33], off
	global_load_ushort v56, v[8:9], off offset:3072
	v_mad_u64_u32 v[8:9], s[8:9], s40, v195, v[4:5]
	v_add_co_u32_e32 v32, vcc, 0x1000, v8
	s_or_b32 s30, s80, 21
	s_nop 0
	v_addc_co_u32_e32 v33, vcc, 0, v9, vcc
	global_load_ushort v73, v[32:33], off
	global_load_ushort v57, v[8:9], off offset:3072
	v_mad_u64_u32 v[8:9], s[8:9], s36, v195, v[4:5]
	v_add_co_u32_e32 v32, vcc, 0x1000, v8
	s_or_b32 s28, s80, 22
	s_nop 0
	v_addc_co_u32_e32 v33, vcc, 0, v9, vcc
	global_load_ushort v75, v[32:33], off
	global_load_ushort v59, v[8:9], off offset:3072
	v_mad_u64_u32 v[8:9], s[8:9], s34, v195, v[4:5]
	v_add_co_u32_e32 v32, vcc, 0x1000, v8
	s_or_b32 s26, s80, 23
	s_nop 0
	v_addc_co_u32_e32 v33, vcc, 0, v9, vcc
	global_load_ushort v72, v[32:33], off
	global_load_ushort v60, v[8:9], off offset:3072
	v_mad_u64_u32 v[8:9], s[8:9], s30, v195, v[4:5]
	v_add_co_u32_e32 v32, vcc, 0x1000, v8
	s_or_b32 s24, s80, 24
	s_nop 0
	v_addc_co_u32_e32 v33, vcc, 0, v9, vcc
	global_load_ushort v70, v[32:33], off
	global_load_ushort v62, v[8:9], off offset:3072
	v_mad_u64_u32 v[8:9], s[8:9], s28, v195, v[4:5]
	v_add_co_u32_e32 v32, vcc, 0x1000, v8
	s_or_b32 s22, s80, 25
	s_nop 0
	v_addc_co_u32_e32 v33, vcc, 0, v9, vcc
	global_load_ushort v67, v[32:33], off
	global_load_ushort v64, v[8:9], off offset:3072
	v_mad_u64_u32 v[8:9], s[8:9], s26, v195, v[4:5]
	v_add_co_u32_e32 v32, vcc, 0x1000, v8
	s_or_b32 s20, s80, 26
	s_nop 0
	v_addc_co_u32_e32 v33, vcc, 0, v9, vcc
	global_load_ushort v68, v[32:33], off
	global_load_ushort v65, v[8:9], off offset:3072
	v_mad_u64_u32 v[8:9], s[8:9], s24, v195, v[4:5]
	v_add_co_u32_e32 v32, vcc, 0x1000, v8
	s_or_b32 s18, s80, 27
	s_nop 0
	v_addc_co_u32_e32 v33, vcc, 0, v9, vcc
	global_load_ushort v55, v[32:33], off
	global_load_ushort v54, v[8:9], off offset:3072
	v_mad_u64_u32 v[8:9], s[8:9], s22, v195, v[4:5]
	v_add_co_u32_e32 v32, vcc, 0x1000, v8
	s_or_b32 s16, s80, 28
	s_nop 0
	v_addc_co_u32_e32 v33, vcc, 0, v9, vcc
	global_load_ushort v53, v[32:33], off
	global_load_ushort v52, v[8:9], off offset:3072
	v_mad_u64_u32 v[8:9], s[8:9], s20, v195, v[4:5]
	v_add_co_u32_e32 v32, vcc, 0x1000, v8
	s_or_b32 s14, s80, 29
	s_nop 0
	v_addc_co_u32_e32 v33, vcc, 0, v9, vcc
	global_load_ushort v44, v[32:33], off
	global_load_ushort v38, v[8:9], off offset:3072
	v_mad_u64_u32 v[8:9], s[8:9], s18, v195, v[4:5]
	v_add_co_u32_e32 v32, vcc, 0x1000, v8
	s_or_b32 s12, s80, 30
	s_nop 0
	v_addc_co_u32_e32 v33, vcc, 0, v9, vcc
	global_load_ushort v47, v[32:33], off
	global_load_ushort v41, v[8:9], off offset:3072
	v_mad_u64_u32 v[8:9], s[8:9], s16, v195, v[4:5]
	v_add_co_u32_e32 v32, vcc, 0x1000, v8
	v_readlane_b32 s81, v254, 63
	s_nop 0
	v_addc_co_u32_e32 v33, vcc, 0, v9, vcc
	global_load_ushort v37, v[32:33], off
	global_load_ushort v36, v[8:9], off offset:3072
	v_readlane_b32 s82, v255, 0
	s_waitcnt vmcnt(0)
	s_add_i32 s8, s1, -15
	s_cmpk_gt_u32 s8, 0xfff
	s_cbranch_scc1 .LBB0_301
	v_lshlrev_b32_e32 v7, 16, v208
	v_mul_f32_e32 v7, 0xbfb8aa3b, v7
	v_exp_f32_e32 v7, v7
	v_lshlrev_b32_e32 v6, 16, v209
	v_add_f32_e32 v7, 1.0, v7
	v_div_scale_f32 v8, s[8:9], v7, v7, v6
	v_rcp_f32_e32 v9, v8
	v_div_scale_f32 v13, vcc, v6, v7, v6
	v_fma_f32 v14, -v8, v9, 1.0
	v_fmac_f32_e32 v9, v14, v9
	v_mul_f32_e32 v14, v13, v9
	v_fma_f32 v15, -v8, v14, v13
	v_fmac_f32_e32 v14, v15, v9
	v_fma_f32 v8, -v8, v14, v13
	v_div_fmas_f32 v8, v8, v9, v14
	v_div_fixup_f32 v28, v8, v7, v6

; __device__ __forceinline__ void conv_tile(const Params& p, int l, int item, const bf16* PROJ, bf16* CV, LAS float* sl) {
;     ...
; #pragma unroll
;     for (int rr = 0; rr < 62; ++rr) { const int sq = s0 - 15 + rr; const bool ok = sq >= 0 && sq < SEQ; const bf16* pr = PROJ + (size_t)(b * SEQ + (ok ? sq : s0)) * NIN;
;         const float a = bf2f(pr[PB_A + c]), g = bf2f(pr[PB_G + c]); u[rr] = ok ? a / (1.0f + __expf(-g)) : 0.f; }
.LBB0_329:
	v_mad_u64_u32 v[8:9], s[8:9], s74, v195, v[4:5]
	v_add_co_u32_e32 v30, vcc, 0x1000, v8
	s_nop 0
	s_nop 0
	v_addc_co_u32_e32 v31, vcc, 0, v9, vcc
	global_load_ushort v97, v[30:31], off
	s_nop 0
	global_load_ushort v30, v[8:9], off offset:3072
	v_mad_u64_u32 v[8:9], s[8:9], s14, v195, v[4:5]
	v_add_co_u32_e32 v32, vcc, 0x1000, v8
	s_nop 0
	s_nop 0
	v_addc_co_u32_e32 v33, vcc, 0, v9, vcc
	global_load_ushort v34, v[32:33], off
	global_load_ushort v13, v[8:9], off offset:3072
	v_mad_u64_u32 v[8:9], s[8:9], s12, v195, v[4:5]
	v_add_co_u32_e32 v32, vcc, 0x1000, v8
	s_or_b32 s8, s80, 31
	s_nop 0
	v_addc_co_u32_e32 v33, vcc, 0, v9, vcc
	global_load_ushort v31, v[32:33], off
	global_load_ushort v29, v[8:9], off offset:3072
	v_mad_u64_u32 v[8:9], s[78:79], s8, v195, v[4:5]
	v_add_co_u32_e32 v32, vcc, 0x1000, v8
	s_cmpk_eq_i32 s1, 0xfe0
	s_nop 0
	v_addc_co_u32_e32 v33, vcc, 0, v9, vcc
	global_load_ushort v33, v[32:33], off
	s_nop 0
	global_load_ushort v32, v[8:9], off offset:3072
	v_readlane_b32 s83, v255, 1
	v_readlane_b32 s84, v255, 2
	v_readlane_b32 s85, v255, 3
	v_readlane_b32 s86, v255, 4
	v_readlane_b32 s87, v255, 5
	v_readlane_b32 s88, v255, 6
	v_readlane_b32 s89, v255, 7
	v_readlane_b32 s90, v255, 8
	v_readlane_b32 s91, v255, 9
	v_readlane_b32 s92, v255, 10
	v_readlane_b32 s93, v255, 11
	v_readlane_b32 s94, v255, 12
	v_readlane_b32 s95, v255, 13
	s_cbranch_scc1 .LBB0_352
	v_lshlrev_b32_e32 v7, 16, v238
	v_mul_f32_e32 v7, 0xbfb8aa3b, v7
	v_exp_f32_e32 v7, v7
	v_lshlrev_b32_e32 v6, 16, v239
	v_add_f32_e32 v7, 1.0, v7
	v_div_scale_f32 v8, s[78:79], v7, v7, v6
	v_rcp_f32_e32 v9, v8
	v_div_scale_f32 v35, vcc, v6, v7, v6
	v_fma_f32 v39, -v8, v9, 1.0
	v_fmac_f32_e32 v9, v39, v9
	v_mul_f32_e32 v39, v35, v9
	v_fma_f32 v40, -v8, v39, v35
	v_fmac_f32_e32 v39, v40, v9
	v_fma_f32 v8, -v8, v39, v35
	v_div_fmas_f32 v8, v8, v9, v39
	v_div_fixup_f32 v6, v8, v7, v6
	v_mov_b32_e32 v7, 0
	s_cmpk_gt_u32 s1, 0xfde
	v_mov_b32_e32 v8, 0
	s_cbranch_scc0 .LBB0_353

; __device__ __forceinline__ void conv_tile(const Params& p, int l, int item, const bf16* PROJ, bf16* CV, LAS float* sl) {
;     ...
; #pragma unroll
;     for (int rr = 0; rr < 62; ++rr) { const int sq = s0 - 15 + rr; const bool ok = sq >= 0 && sq < SEQ; const bf16* pr = PROJ + (size_t)(b * SEQ + (ok ? sq : s0)) * NIN;
;         const float a = bf2f(pr[PB_A + c]), g = bf2f(pr[PB_G + c]); u[rr] = ok ? a / (1.0f + __expf(-g)) : 0.f; }
.LBB0_345:
	s_waitcnt vmcnt(8)
	v_lshlrev_b32_e32 v4, 16, v102
	v_mul_f32_e32 v4, 0xbfb8aa3b, v4
	v_exp_f32_e32 v4, v4
	v_lshlrev_b32_e32 v5, 16, v101
	s_waitcnt vmcnt(8)
	v_lshlrev_b32_e32 v100, 16, v100
	v_mul_f32_e32 v100, 0xbfb8aa3b, v100
	v_add_f32_e32 v4, 1.0, v4
	v_div_scale_f32 v101, s[0:1], v4, v4, v5
	v_rcp_f32_e32 v102, v101
	v_exp_f32_e32 v100, v100
	v_div_scale_f32 v103, vcc, v5, v4, v5
	v_fma_f32 v104, -v101, v102, 1.0
	v_fmac_f32_e32 v102, v104, v102
	v_mul_f32_e32 v104, v103, v102
	v_fma_f32 v105, -v101, v104, v103
	v_fmac_f32_e32 v104, v105, v102
	s_waitcnt vmcnt(8)
	v_lshlrev_b32_e32 v99, 16, v99
	v_add_f32_e32 v100, 1.0, v100
	v_fma_f32 v101, -v101, v104, v103
	v_div_scale_f32 v103, s[0:1], v100, v100, v99
	v_rcp_f32_e32 v105, v103
	s_waitcnt vmcnt(7)
	v_lshlrev_b32_e32 v97, 16, v97
	v_mul_f32_e32 v97, 0xbfb8aa3b, v97
	v_div_fmas_f32 v101, v101, v102, v104
	v_exp_f32_e32 v97, v97
	v_div_fixup_f32 v121, v101, v4, v5
	v_fma_f32 v4, -v103, v105, 1.0
	v_fmac_f32_e32 v105, v4, v105
	v_div_scale_f32 v4, vcc, v99, v100, v99
	v_mul_f32_e32 v5, v4, v105
	v_fma_f32 v101, -v103, v5, v4
	s_waitcnt vmcnt(6)
	v_lshlrev_b32_e32 v30, 16, v30
	v_add_f32_e32 v97, 1.0, v97
	v_fmac_f32_e32 v5, v101, v105
	v_div_scale_f32 v101, s[0:1], v97, v97, v30
	v_rcp_f32_e32 v102, v101
	s_waitcnt vmcnt(6)
	v_lshlrev_b32_e32 v98, 16, v98
	v_fma_f32 v4, -v103, v5, v4
	v_mul_f32_e32 v98, 0xbfb8aa3b, v98
	v_div_fmas_f32 v4, v4, v105, v5
	v_exp_f32_e32 v98, v98
	v_div_fixup_f32 v119, v4, v100, v99
	v_fma_f32 v4, -v101, v102, 1.0
	v_fmac_f32_e32 v102, v4, v102
	v_div_scale_f32 v4, vcc, v30, v97, v30
	v_mul_f32_e32 v5, v4, v102
	v_fma_f32 v99, -v101, v5, v4
	s_waitcnt vmcnt(6)
	v_lshlrev_b32_e32 v96, 16, v96
	v_add_f32_e32 v98, 1.0, v98
	v_fmac_f32_e32 v5, v99, v102
	v_div_scale_f32 v99, s[0:1], v98, v98, v96
	v_rcp_f32_e32 v100, v99
	s_waitcnt vmcnt(6)
	v_lshlrev_b32_e32 v95, 16, v95
	v_fma_f32 v4, -v101, v5, v4
	v_mul_f32_e32 v95, 0xbfb8aa3b, v95
	v_div_fmas_f32 v4, v4, v102, v5
	v_exp_f32_e32 v95, v95
	v_div_fixup_f32 v30, v4, v97, v30
	v_fma_f32 v4, -v99, v100, 1.0
	v_fmac_f32_e32 v100, v4, v100
	v_div_scale_f32 v4, vcc, v96, v98, v96
	v_mul_f32_e32 v5, v4, v100
	v_fma_f32 v97, -v99, v5, v4
	s_waitcnt vmcnt(6)
	v_lshlrev_b32_e32 v94, 16, v94
	v_add_f32_e32 v95, 1.0, v95
	v_fmac_f32_e32 v5, v97, v100
	v_div_scale_f32 v97, s[0:1], v95, v95, v94
	v_fma_f32 v4, -v99, v5, v4
	v_rcp_f32_e32 v99, v97
	s_waitcnt vmcnt(6)
	v_lshlrev_b32_e32 v93, 16, v93
	v_div_fmas_f32 v4, v4, v100, v5
	v_mul_f32_e32 v93, 0xbfb8aa3b, v93
	v_div_fixup_f32 v111, v4, v98, v96
	v_fma_f32 v4, -v97, v99, 1.0
	v_exp_f32_e32 v93, v93
	v_fmac_f32_e32 v99, v4, v99
	v_div_scale_f32 v4, vcc, v94, v95, v94
	v_mul_f32_e32 v5, v4, v99
	v_fma_f32 v96, -v97, v5, v4
	v_fmac_f32_e32 v5, v96, v99
	s_waitcnt vmcnt(6)
	v_lshlrev_b32_e32 v96, 16, v91
	v_add_f32_e32 v93, 1.0, v93
	v_fma_f32 v4, -v97, v5, v4
	v_div_scale_f32 v97, s[0:1], v93, v93, v96
	v_rcp_f32_e32 v98, v97
	s_waitcnt vmcnt(6)
	v_lshlrev_b32_e32 v90, 16, v90
	v_div_fmas_f32 v4, v4, v99, v5
	v_mul_f32_e32 v90, 0xbfb8aa3b, v90
	v_div_fixup_f32 v91, v4, v95, v94
	v_fma_f32 v4, -v97, v98, 1.0
	v_exp_f32_e32 v90, v90
	v_fmac_f32_e32 v98, v4, v98
	v_div_scale_f32 v4, vcc, v96, v93, v96
	v_mul_f32_e32 v5, v4, v98
	v_fma_f32 v94, -v97, v5, v4
	v_fmac_f32_e32 v5, v94, v98
	s_waitcnt vmcnt(6)
	v_lshlrev_b32_e32 v81, 16, v81
	v_add_f32_e32 v94, 1.0, v90
	v_div_scale_f32 v95, s[0:1], v94, v94, v81
	v_fma_f32 v4, -v97, v5, v4
	v_rcp_f32_e32 v97, v95
	s_waitcnt vmcnt(6)
	v_lshlrev_b32_e32 v92, 16, v92
	v_mul_f32_e32 v92, 0xbfb8aa3b, v92
	v_div_fmas_f32 v4, v4, v98, v5
	v_exp_f32_e32 v92, v92
	v_div_fixup_f32 v90, v4, v93, v96
	v_fma_f32 v4, -v95, v97, 1.0
	v_fmac_f32_e32 v97, v4, v97
	v_div_scale_f32 v4, vcc, v81, v94, v81
	v_mul_f32_e32 v5, v4, v97
	v_fma_f32 v93, -v95, v5, v4
	s_waitcnt vmcnt(6)
	v_lshlrev_b32_e32 v89, 16, v89
	v_add_f32_e32 v92, 1.0, v92
	v_fmac_f32_e32 v5, v93, v97
	v_div_scale_f32 v93, s[0:1], v92, v92, v89
	v_fma_f32 v4, -v95, v5, v4
	v_rcp_f32_e32 v95, v93
	v_div_fmas_f32 v4, v4, v97, v5
	s_waitcnt vmcnt(6)
	v_lshlrev_b32_e32 v88, 16, v88
	v_div_fixup_f32 v81, v4, v94, v81
	v_fma_f32 v4, -v93, v95, 1.0
	v_mul_f32_e32 v88, 0xbfb8aa3b, v88
	v_fmac_f32_e32 v95, v4, v95
	v_div_scale_f32 v4, vcc, v89, v92, v89
	v_exp_f32_e32 v88, v88
	v_mul_f32_e32 v5, v4, v95
	v_fma_f32 v94, -v93, v5, v4
	v_fmac_f32_e32 v5, v94, v95
	v_fma_f32 v4, -v93, v5, v4
	s_waitcnt vmcnt(6)
	v_lshlrev_b32_e32 v93, 16, v77
	v_add_f32_e32 v88, 1.0, v88
	v_div_scale_f32 v94, s[0:1], v88, v88, v93
	v_rcp_f32_e32 v96, v94
	s_waitcnt vmcnt(6)
	v_lshlrev_b32_e32 v87, 16, v87
	v_div_fmas_f32 v4, v4, v95, v5
	v_mul_f32_e32 v87, 0xbfb8aa3b, v87
	v_div_fixup_f32 v77, v4, v92, v89
	v_fma_f32 v4, -v94, v96, 1.0
	v_exp_f32_e32 v87, v87
	v_fmac_f32_e32 v96, v4, v96
	v_div_scale_f32 v4, vcc, v93, v88, v93
	v_mul_f32_e32 v5, v4, v96
	v_fma_f32 v89, -v94, v5, v4
	v_fmac_f32_e32 v5, v89, v96
	s_waitcnt vmcnt(6)
	v_lshlrev_b32_e32 v89, 16, v76
	v_add_f32_e32 v87, 1.0, v87
	v_div_scale_f32 v92, s[0:1], v87, v87, v89
	v_fma_f32 v4, -v94, v5, v4
	v_rcp_f32_e32 v94, v92
	s_waitcnt vmcnt(6)
	v_lshlrev_b32_e32 v74, 16, v74
	v_div_fmas_f32 v4, v4, v96, v5
	v_mul_f32_e32 v74, 0xbfb8aa3b, v74
	v_div_fixup_f32 v76, v4, v88, v93
	v_fma_f32 v4, -v92, v94, 1.0
	v_exp_f32_e32 v74, v74
	v_fmac_f32_e32 v94, v4, v94
	v_div_scale_f32 v4, vcc, v89, v87, v89
	v_mul_f32_e32 v5, v4, v94
	v_fma_f32 v88, -v92, v5, v4
	v_fmac_f32_e32 v5, v88, v94
	s_waitcnt vmcnt(6)
	v_lshlrev_b32_e32 v71, 16, v71
	v_add_f32_e32 v88, 1.0, v74
	v_fma_f32 v4, -v92, v5, v4
	v_div_scale_f32 v92, s[0:1], v88, v88, v71
	v_rcp_f32_e32 v93, v92
	s_waitcnt vmcnt(6)
; __device__ __forceinline__ void conv_tile(const Params& p, int l, int item, const bf16* PROJ, bf16* CV, LAS float* sl) {
;     ...
; #pragma unroll
;     for (int rr = 0; rr < 62; ++rr) { const int sq = s0 - 15 + rr; const bool ok = sq >= 0 && sq < SEQ; const bf16* pr = PROJ + (size_t)(b * SEQ + (ok ? sq : s0)) * NIN;
;         const float a = bf2f(pr[PB_A + c]), g = bf2f(pr[PB_G + c]); u[rr] = ok ? a / (1.0f + __expf(-g)) : 0.f; }
	v_lshlrev_b32_e32 v86, 16, v86
	v_mul_f32_e32 v86, 0xbfb8aa3b, v86
	v_div_fmas_f32 v4, v4, v94, v5
	v_exp_f32_e32 v86, v86
	v_div_fixup_f32 v74, v4, v87, v89
	v_fma_f32 v4, -v92, v93, 1.0
	v_fmac_f32_e32 v93, v4, v93
	v_div_scale_f32 v4, vcc, v71, v88, v71
	v_mul_f32_e32 v5, v4, v93
	v_fma_f32 v87, -v92, v5, v4
	s_waitcnt vmcnt(6)
	v_lshlrev_b32_e32 v85, 16, v85
	v_add_f32_e32 v86, 1.0, v86
	v_fmac_f32_e32 v5, v87, v93
	v_div_scale_f32 v87, s[0:1], v86, v86, v85
	v_rcp_f32_e32 v89, v87
	v_fma_f32 v4, -v92, v5, v4
	v_div_fmas_f32 v4, v4, v93, v5
	s_waitcnt vmcnt(6)
	v_lshlrev_b32_e32 v84, 16, v84
	v_div_fixup_f32 v71, v4, v88, v71
	v_fma_f32 v4, -v87, v89, 1.0
	v_mul_f32_e32 v84, 0xbfb8aa3b, v84
	v_fmac_f32_e32 v89, v4, v89
	v_div_scale_f32 v4, vcc, v85, v86, v85
	v_exp_f32_e32 v84, v84
	v_mul_f32_e32 v5, v4, v89
	v_fma_f32 v88, -v87, v5, v4
	v_fmac_f32_e32 v5, v88, v89
	v_fma_f32 v4, -v87, v5, v4
	s_waitcnt vmcnt(6)
	v_lshlrev_b32_e32 v87, 16, v69
	v_add_f32_e32 v84, 1.0, v84
	v_div_scale_f32 v88, s[0:1], v84, v84, v87
	v_rcp_f32_e32 v92, v88
	s_waitcnt vmcnt(6)
	v_lshlrev_b32_e32 v83, 16, v83
	v_div_fmas_f32 v4, v4, v89, v5
	v_mul_f32_e32 v83, 0xbfb8aa3b, v83
	v_div_fixup_f32 v69, v4, v86, v85
	v_fma_f32 v4, -v88, v92, 1.0
	v_exp_f32_e32 v83, v83
	v_fmac_f32_e32 v92, v4, v92
	v_div_scale_f32 v4, vcc, v87, v84, v87
	v_mul_f32_e32 v5, v4, v92
	v_fma_f32 v85, -v88, v5, v4
	v_fmac_f32_e32 v5, v85, v92
	s_waitcnt vmcnt(6)
	v_lshlrev_b32_e32 v85, 16, v66
	v_add_f32_e32 v83, 1.0, v83
	v_div_scale_f32 v86, s[0:1], v83, v83, v85
	v_fma_f32 v4, -v88, v5, v4
	v_rcp_f32_e32 v88, v86
	s_waitcnt vmcnt(6)
	v_lshlrev_b32_e32 v63, 16, v63
	v_div_fmas_f32 v4, v4, v92, v5
	v_mul_f32_e32 v63, 0xbfb8aa3b, v63
	v_div_fixup_f32 v66, v4, v84, v87
	v_fma_f32 v4, -v86, v88, 1.0
	v_exp_f32_e32 v63, v63
	v_fmac_f32_e32 v88, v4, v88
	v_div_scale_f32 v4, vcc, v85, v83, v85
	v_mul_f32_e32 v5, v4, v88
	v_fma_f32 v84, -v86, v5, v4
	v_fmac_f32_e32 v5, v84, v88
	s_waitcnt vmcnt(6)
	v_lshlrev_b32_e32 v61, 16, v61
	v_add_f32_e32 v84, 1.0, v63
	v_fma_f32 v4, -v86, v5, v4
	v_div_scale_f32 v86, s[0:1], v84, v84, v61
	v_rcp_f32_e32 v87, v86
	s_waitcnt vmcnt(6)
	v_lshlrev_b32_e32 v82, 16, v82
	v_mul_f32_e32 v82, 0xbfb8aa3b, v82
	v_div_fmas_f32 v4, v4, v88, v5
	v_exp_f32_e32 v82, v82
	v_div_fixup_f32 v63, v4, v83, v85
	v_fma_f32 v4, -v86, v87, 1.0
	v_fmac_f32_e32 v87, v4, v87
	v_div_scale_f32 v4, vcc, v61, v84, v61
	v_mul_f32_e32 v5, v4, v87
	v_fma_f32 v83, -v86, v5, v4
	s_waitcnt vmcnt(6)
	v_lshlrev_b32_e32 v80, 16, v80
	v_add_f32_e32 v82, 1.0, v82
	v_fmac_f32_e32 v5, v83, v87
	v_div_scale_f32 v83, s[0:1], v82, v82, v80
	v_rcp_f32_e32 v85, v83
	v_fma_f32 v4, -v86, v5, v4
	v_div_fmas_f32 v4, v4, v87, v5
	s_waitcnt vmcnt(6)
	v_lshlrev_b32_e32 v79, 16, v79
	v_div_fixup_f32 v61, v4, v84, v61
	v_fma_f32 v4, -v83, v85, 1.0
	v_mul_f32_e32 v79, 0xbfb8aa3b, v79
	v_fmac_f32_e32 v85, v4, v85
	v_div_scale_f32 v4, vcc, v80, v82, v80
	v_exp_f32_e32 v79, v79
	v_mul_f32_e32 v5, v4, v85
	v_fma_f32 v84, -v83, v5, v4
	v_fmac_f32_e32 v5, v84, v85
	v_fma_f32 v4, -v83, v5, v4
	s_waitcnt vmcnt(6)
	v_lshlrev_b32_e32 v83, 16, v58
	v_add_f32_e32 v79, 1.0, v79
	v_div_scale_f32 v84, s[0:1], v79, v79, v83
	v_rcp_f32_e32 v86, v84
	s_waitcnt vmcnt(6)
	v_lshlrev_b32_e32 v78, 16, v78
	v_div_fmas_f32 v4, v4, v85, v5
	v_mul_f32_e32 v78, 0xbfb8aa3b, v78
	v_div_fixup_f32 v58, v4, v82, v80
	v_fma_f32 v4, -v84, v86, 1.0
	v_exp_f32_e32 v78, v78
	v_fmac_f32_e32 v86, v4, v86
	v_div_scale_f32 v4, vcc, v83, v79, v83
	v_mul_f32_e32 v5, v4, v86
	v_fma_f32 v80, -v84, v5, v4
	v_fmac_f32_e32 v5, v80, v86
	s_waitcnt vmcnt(6)
	v_lshlrev_b32_e32 v80, 16, v56
	v_add_f32_e32 v78, 1.0, v78
	v_div_scale_f32 v82, s[0:1], v78, v78, v80
	v_fma_f32 v4, -v84, v5, v4
	v_rcp_f32_e32 v84, v82
	s_waitcnt vmcnt(6)
	v_lshlrev_b32_e32 v73, 16, v73
	v_div_fmas_f32 v4, v4, v86, v5
	v_mul_f32_e32 v73, 0xbfb8aa3b, v73
	v_div_fixup_f32 v56, v4, v79, v83
	v_fma_f32 v4, -v82, v84, 1.0
	v_exp_f32_e32 v73, v73
	v_fmac_f32_e32 v84, v4, v84
	v_div_scale_f32 v4, vcc, v80, v78, v80
	v_mul_f32_e32 v5, v4, v84
	v_fma_f32 v79, -v82, v5, v4
	v_fmac_f32_e32 v5, v79, v84
	s_waitcnt vmcnt(6)
	v_lshlrev_b32_e32 v79, 16, v57
	v_add_f32_e32 v73, 1.0, v73
	v_fma_f32 v4, -v82, v5, v4
	v_div_scale_f32 v82, s[0:1], v73, v73, v79
	v_rcp_f32_e32 v83, v82
	s_waitcnt vmcnt(6)
	v_lshlrev_b32_e32 v75, 16, v75
	v_div_fmas_f32 v4, v4, v84, v5
	v_mul_f32_e32 v75, 0xbfb8aa3b, v75
	v_div_fixup_f32 v57, v4, v78, v80
	v_fma_f32 v4, -v82, v83, 1.0
	v_exp_f32_e32 v75, v75
	v_fmac_f32_e32 v83, v4, v83
	v_div_scale_f32 v4, vcc, v79, v73, v79
	v_mul_f32_e32 v5, v4, v83
	v_fma_f32 v78, -v82, v5, v4
	v_fmac_f32_e32 v5, v78, v83
	s_waitcnt vmcnt(6)
	v_lshlrev_b32_e32 v78, 16, v59
	v_add_f32_e32 v75, 1.0, v75
	v_div_scale_f32 v80, s[0:1], v75, v75, v78
	v_fma_f32 v4, -v82, v5, v4
	v_rcp_f32_e32 v82, v80
	s_waitcnt vmcnt(6)
	v_lshlrev_b32_e32 v72, 16, v72
	v_div_fmas_f32 v4, v4, v83, v5
	v_mul_f32_e32 v72, 0xbfb8aa3b, v72
	v_div_fixup_f32 v59, v4, v73, v79
	v_fma_f32 v4, -v80, v82, 1.0
	v_exp_f32_e32 v72, v72
	v_fmac_f32_e32 v82, v4, v82
	v_div_scale_f32 v4, vcc, v78, v75, v78
	v_mul_f32_e32 v5, v4, v82
	v_fma_f32 v73, -v80, v5, v4
	v_fmac_f32_e32 v5, v73, v82
	s_waitcnt vmcnt(6)
	v_lshlrev_b32_e32 v73, 16, v60
	v_add_f32_e32 v72, 1.0, v72
	v_div_scale_f32 v79, s[0:1], v72, v72, v73
	v_fma_f32 v4, -v80, v5, v4
	v_rcp_f32_e32 v80, v79
	s_waitcnt vmcnt(6)
	v_lshlrev_b32_e32 v70, 16, v70
	v_div_fmas_f32 v4, v4, v82, v5
	v_mul_f32_e32 v70, 0xbfb8aa3b, v70
	v_div_fixup_f32 v60, v4, v75, v78
	v_fma_f32 v4, -v79, v80, 1.0
	v_exp_f32_e32 v70, v70
	v_fmac_f32_e32 v80, v4, v80
	v_div_scale_f32 v4, vcc, v73, v72, v73
	v_mul_f32_e32 v5, v4, v80
	v_fma_f32 v75, -v79, v5, v4
	v_fmac_f32_e32 v5, v75, v80
	s_waitcnt vmcnt(6)
; __device__ __forceinline__ void conv_tile(const Params& p, int l, int item, const bf16* PROJ, bf16* CV, LAS float* sl) {
;     ...
; #pragma unroll
;     for (int rr = 0; rr < 62; ++rr) { const int sq = s0 - 15 + rr; const bool ok = sq >= 0 && sq < SEQ; const bf16* pr = PROJ + (size_t)(b * SEQ + (ok ? sq : s0)) * NIN;
;         const float a = bf2f(pr[PB_A + c]), g = bf2f(pr[PB_G + c]); u[rr] = ok ? a / (1.0f + __expf(-g)) : 0.f; }
;     float w[31];
; #pragma unroll
;     for (int j = 0; j < 31; ++j) w[j] = p.conv_dw[(size_t)(l * 31 + j) * CC + c];
	v_lshlrev_b32_e32 v75, 16, v62
	v_add_f32_e32 v70, 1.0, v70
	v_div_scale_f32 v78, s[0:1], v70, v70, v75
	v_fma_f32 v4, -v79, v5, v4
	v_rcp_f32_e32 v79, v78
	s_waitcnt vmcnt(6)
	v_lshlrev_b32_e32 v67, 16, v67
	v_div_fmas_f32 v4, v4, v80, v5
	v_mul_f32_e32 v67, 0xbfb8aa3b, v67
	v_div_fixup_f32 v62, v4, v72, v73
	v_fma_f32 v4, -v78, v79, 1.0
	v_exp_f32_e32 v67, v67
	v_fmac_f32_e32 v79, v4, v79
	v_div_scale_f32 v4, vcc, v75, v70, v75
	v_mul_f32_e32 v5, v4, v79
	v_fma_f32 v72, -v78, v5, v4
	v_fmac_f32_e32 v5, v72, v79
	s_waitcnt vmcnt(6)
	v_lshlrev_b32_e32 v72, 16, v64
	v_add_f32_e32 v67, 1.0, v67
	v_div_scale_f32 v73, s[0:1], v67, v67, v72
	v_fma_f32 v4, -v78, v5, v4
	v_rcp_f32_e32 v78, v73
	s_waitcnt vmcnt(6)
	v_lshlrev_b32_e32 v68, 16, v68
	v_div_fmas_f32 v4, v4, v79, v5
	v_mul_f32_e32 v68, 0xbfb8aa3b, v68
	v_div_fixup_f32 v64, v4, v70, v75
	v_fma_f32 v4, -v73, v78, 1.0
	v_exp_f32_e32 v68, v68
	v_fmac_f32_e32 v78, v4, v78
	v_div_scale_f32 v4, vcc, v72, v67, v72
	v_mul_f32_e32 v5, v4, v78
	v_fma_f32 v70, -v73, v5, v4
	v_fmac_f32_e32 v5, v70, v78
	s_waitcnt vmcnt(6)
	v_lshlrev_b32_e32 v70, 16, v65
	v_add_f32_e32 v68, 1.0, v68
	v_fma_f32 v4, -v73, v5, v4
	v_div_scale_f32 v73, s[0:1], v68, v68, v70
	v_rcp_f32_e32 v75, v73
	s_waitcnt vmcnt(6)
	v_lshlrev_b32_e32 v55, 16, v55
	v_mul_f32_e32 v55, 0xbfb8aa3b, v55
	v_div_fmas_f32 v4, v4, v78, v5
	v_exp_f32_e32 v55, v55
	v_div_fixup_f32 v65, v4, v67, v72
	v_fma_f32 v4, -v73, v75, 1.0
	v_fmac_f32_e32 v75, v4, v75
	v_div_scale_f32 v4, vcc, v70, v68, v70
	v_mul_f32_e32 v5, v4, v75
	v_fma_f32 v67, -v73, v5, v4
	s_waitcnt vmcnt(6)
	v_lshlrev_b32_e32 v54, 16, v54
	v_add_f32_e32 v55, 1.0, v55
	v_fmac_f32_e32 v5, v67, v75
	v_div_scale_f32 v72, s[0:1], v55, v55, v54
	v_fma_f32 v4, -v73, v5, v4
	v_rcp_f32_e32 v73, v72
	s_waitcnt vmcnt(6)
	v_lshlrev_b32_e32 v53, 16, v53
	v_mul_f32_e32 v53, 0xbfb8aa3b, v53
	v_div_fmas_f32 v4, v4, v75, v5
	v_exp_f32_e32 v53, v53
	v_div_fixup_f32 v67, v4, v68, v70
	v_fma_f32 v4, -v72, v73, 1.0
	v_fmac_f32_e32 v73, v4, v73
	v_div_scale_f32 v4, vcc, v54, v55, v54
	v_mul_f32_e32 v5, v4, v73
	v_fma_f32 v68, -v72, v5, v4
	s_waitcnt vmcnt(6)
	v_lshlrev_b32_e32 v52, 16, v52
	v_add_f32_e32 v53, 1.0, v53
	v_fmac_f32_e32 v5, v68, v73
	v_div_scale_f32 v70, s[0:1], v53, v53, v52
	v_fma_f32 v4, -v72, v5, v4
	v_rcp_f32_e32 v72, v70
	s_waitcnt vmcnt(6)
	v_lshlrev_b32_e32 v44, 16, v44
	v_mul_f32_e32 v44, 0xbfb8aa3b, v44
	v_div_fmas_f32 v4, v4, v73, v5
	v_exp_f32_e32 v44, v44
	v_div_fixup_f32 v68, v4, v55, v54
	v_fma_f32 v4, -v70, v72, 1.0
	v_fmac_f32_e32 v72, v4, v72
	v_div_scale_f32 v4, vcc, v52, v53, v52
	v_mul_f32_e32 v5, v4, v72
	v_fma_f32 v54, -v70, v5, v4
	s_waitcnt vmcnt(6)
	v_lshlrev_b32_e32 v38, 16, v38
	v_add_f32_e32 v44, 1.0, v44
	v_fmac_f32_e32 v5, v54, v72
	v_div_scale_f32 v54, s[0:1], v44, v44, v38
	v_rcp_f32_e32 v55, v54
	s_waitcnt vmcnt(6)
	v_lshlrev_b32_e32 v47, 16, v47
	v_fma_f32 v4, -v70, v5, v4
	v_mul_f32_e32 v47, 0xbfb8aa3b, v47
	v_div_fmas_f32 v4, v4, v72, v5
	v_exp_f32_e32 v47, v47
	v_div_fixup_f32 v70, v4, v53, v52
	v_fma_f32 v4, -v54, v55, 1.0
	v_fmac_f32_e32 v55, v4, v55
	v_div_scale_f32 v4, vcc, v38, v44, v38
	v_mul_f32_e32 v5, v4, v55
	v_fma_f32 v52, -v54, v5, v4
	s_waitcnt vmcnt(6)
	v_lshlrev_b32_e32 v41, 16, v41
	v_add_f32_e32 v47, 1.0, v47
	v_fmac_f32_e32 v5, v52, v55
	v_div_scale_f32 v52, s[0:1], v47, v47, v41
	v_rcp_f32_e32 v53, v52
	s_waitcnt vmcnt(6)
	v_lshlrev_b32_e32 v37, 16, v37
	v_fma_f32 v4, -v54, v5, v4
	v_mul_f32_e32 v37, 0xbfb8aa3b, v37
	v_div_fmas_f32 v4, v4, v55, v5
	v_exp_f32_e32 v37, v37
	v_div_fixup_f32 v72, v4, v44, v38
	v_fma_f32 v4, -v52, v53, 1.0
	v_fmac_f32_e32 v53, v4, v53
	v_div_scale_f32 v4, vcc, v41, v47, v41
	v_mul_f32_e32 v5, v4, v53
	v_fma_f32 v38, -v52, v5, v4
	s_waitcnt vmcnt(6)
	v_lshlrev_b32_e32 v36, 16, v36
	v_add_f32_e32 v37, 1.0, v37
	v_fmac_f32_e32 v5, v38, v53
	v_div_scale_f32 v38, s[0:1], v37, v37, v36
	v_rcp_f32_e32 v44, v38
	v_fma_f32 v4, -v52, v5, v4
	v_div_fmas_f32 v4, v4, v53, v5
	s_waitcnt vmcnt(5)
	v_lshlrev_b32_e32 v34, 16, v34
	v_div_fixup_f32 v73, v4, v47, v41
	v_fma_f32 v4, -v38, v44, 1.0
	v_mul_f32_e32 v34, 0xbfb8aa3b, v34
	v_fmac_f32_e32 v44, v4, v44
	v_div_scale_f32 v4, vcc, v36, v37, v36
	v_exp_f32_e32 v34, v34
	v_mul_f32_e32 v5, v4, v44
	v_fma_f32 v41, -v38, v5, v4
	v_fmac_f32_e32 v5, v41, v44
	v_fma_f32 v4, -v38, v5, v4
	s_waitcnt vmcnt(4)
	v_lshlrev_b32_e32 v38, 16, v13
	v_add_f32_e32 v34, 1.0, v34
	v_div_scale_f32 v41, s[0:1], v34, v34, v38
	v_div_fmas_f32 v4, v4, v44, v5
	v_div_fixup_f32 v75, v4, v37, v36
	v_lshl_add_u64 v[36:37], v[2:3], 2, s[2:3]
	s_movk_i32 s0, 0x1000
	v_add_co_u32_e32 v4, vcc, s0, v36
	s_movk_i32 s0, 0x2000
	s_nop 0
	v_addc_co_u32_e32 v5, vcc, 0, v37, vcc
	v_add_co_u32_e32 v52, vcc, s0, v36
	s_movk_i32 s0, 0x3000
	s_nop 0
	v_addc_co_u32_e32 v53, vcc, 0, v37, vcc
	v_add_co_u32_e32 v54, vcc, s0, v36
	s_movk_i32 s0, 0x4000
	s_nop 0
	v_addc_co_u32_e32 v55, vcc, 0, v37, vcc
	s_waitcnt vmcnt(0)
; __device__ __forceinline__ void conv_tile(const Params& p, int l, int item, const bf16* PROJ, bf16* CV, LAS float* sl) {
;     ...
;         const float a = bf2f(pr[PB_A + c]), g = bf2f(pr[PB_G + c]); u[rr] = ok ? a / (1.0f + __expf(-g)) : 0.f; }
;     float w[31];
; #pragma unroll
;     for (int j = 0; j < 31; ++j) w[j] = p.conv_dw[(size_t)(l * 31 + j) * CC + c];
;     const float bias = p.conv_dw_b[l * CC + c];
;     float y[32], y2[32];
; #pragma unroll
;     for (int t = 0; t < 32; ++t) { float acc = bias;
; #pragma unroll
;         for (int j = 0; j < 31; ++j) acc = fmaf(u[t + j], w[j], acc);
;         y[t] = acc; y2[t] = acc * acc; }
	global_load_dword v80, v[36:37], off
	global_load_dword v79, v[36:37], off offset:2048
	global_load_dword v78, v[4:5], off offset:2048
	v_add_co_u32_e32 v4, vcc, s0, v36
	s_movk_i32 s0, 0x5000
	s_nop 0
	v_addc_co_u32_e32 v5, vcc, 0, v37, vcc
	v_add_co_u32_e32 v96, vcc, s0, v36
	s_movk_i32 s0, 0x6000
	s_nop 0
	v_addc_co_u32_e32 v97, vcc, 0, v37, vcc
	v_add_co_u32_e32 v92, vcc, s0, v36
	s_movk_i32 s0, 0x7000
	s_nop 0
	v_addc_co_u32_e32 v93, vcc, 0, v37, vcc
	global_load_dword v89, v[52:53], off offset:-4096
	global_load_dword v88, v[52:53], off
	global_load_dword v87, v[52:53], off offset:2048
	global_load_dword v86, v[4:5], off offset:-4096
	global_load_dword v84, v[4:5], off
	global_load_dword v83, v[4:5], off offset:2048
	global_load_dword v85, v[92:93], off offset:-4096
	global_load_dword v82, v[92:93], off
	v_add_co_u32_e32 v52, vcc, s0, v36
	s_mov_b32 s0, 0x8000
	s_nop 0
	v_addc_co_u32_e32 v53, vcc, 0, v37, vcc
	v_add_co_u32_e32 v94, vcc, s0, v36
	s_mov_b32 s0, 0x9000
	s_nop 0
	v_addc_co_u32_e32 v95, vcc, 0, v37, vcc
	v_add_co_u32_e32 v114, vcc, s0, v36
	s_mov_b32 s0, 0xa000
	s_nop 0
	v_addc_co_u32_e32 v115, vcc, 0, v37, vcc
	v_add_co_u32_e32 v108, vcc, s0, v36
	s_mov_b32 s0, 0xb000
	s_nop 0
	v_addc_co_u32_e32 v109, vcc, 0, v37, vcc
	v_add_co_u32_e32 v116, vcc, s0, v36
	s_mov_b32 s0, 0xc000
	s_nop 0
	v_addc_co_u32_e32 v117, vcc, 0, v37, vcc
	v_add_co_u32_e32 v122, vcc, s0, v36
	v_readlane_b32 s0, v255, 24
	v_readlane_b32 s80, v251, 33
	v_readlane_b32 s84, v251, 37
	v_add_u32_e32 v4, s0, v2
	v_ashrrev_i32_e32 v5, 31, v4
	v_readlane_b32 s85, v251, 38
	v_addc_co_u32_e32 v123, vcc, 0, v37, vcc
	s_nop 0
	v_lshl_add_u64 v[98:99], v[4:5], 2, s[84:85]
	global_load_dword v13, v[98:99], off
	global_load_dword v107, v[92:93], off offset:2048
	global_load_dword v105, v[94:95], off offset:-4096
	global_load_dword v102, v[94:95], off
	global_load_dword v101, v[94:95], off offset:2048
	s_nop 0
	global_load_dword v98, v[108:109], off offset:-4096
	global_load_dword v94, v[108:109], off
	global_load_dword v93, v[108:109], off offset:2048
	global_load_dword v92, v[122:123], off offset:-4096
	global_load_dword v112, v[54:55], off offset:2048
	global_load_dword v110, v[96:97], off offset:2048
	s_nop 0
	global_load_dword v109, v[52:53], off offset:2048
	global_load_dword v108, v[114:115], off offset:2048
	global_load_dword v96, v[116:117], off offset:2048
	s_mov_b32 s0, 0xd000
	v_add_co_u32_e32 v52, vcc, s0, v36
	s_mov_b32 s0, 0xe000
	s_nop 0
	v_addc_co_u32_e32 v53, vcc, 0, v37, vcc
	v_add_co_u32_e32 v54, vcc, s0, v36
	s_mov_b32 s0, 0xf000
	s_nop 0
	v_addc_co_u32_e32 v55, vcc, 0, v37, vcc
	global_load_dword v95, v[52:53], off offset:2048
	global_load_dword v106, v[122:123], off
	global_load_dword v104, v[122:123], off offset:2048
	global_load_dword v103, v[54:55], off offset:-4096
	global_load_dword v99, v[54:55], off
	global_load_dword v97, v[54:55], off offset:2048
	v_add_co_u32_e32 v36, vcc, s0, v36
	v_rcp_f32_e32 v47, v41
	s_nop 0
	v_addc_co_u32_e32 v37, vcc, 0, v37, vcc
	global_load_dword v100, v[36:37], off
	s_waitcnt vmcnt(35)
	v_lshlrev_b32_e32 v31, 16, v31
	v_mul_f32_e32 v31, 0xbfb8aa3b, v31
	v_fma_f32 v44, -v41, v47, 1.0
	v_exp_f32_e32 v31, v31
	v_fmac_f32_e32 v47, v44, v47
	v_div_scale_f32 v36, vcc, v38, v34, v38
	v_mul_f32_e32 v37, v36, v47
	v_fma_f32 v44, -v41, v37, v36
	v_readlane_b32 s1, v255, 25
	v_fmac_f32_e32 v37, v44, v47
	s_waitcnt vmcnt(34)
	v_lshlrev_b32_e32 v29, 16, v29
	v_add_f32_e32 v31, 1.0, v31
	v_fma_f32 v36, -v41, v37, v36
	v_div_scale_f32 v41, s[0:1], v31, v31, v29
	v_rcp_f32_e32 v44, v41
	s_waitcnt vmcnt(33)
	v_lshlrev_b32_e32 v33, 16, v33
	v_mul_f32_e32 v33, 0xbfb8aa3b, v33
	v_div_fmas_f32 v36, v36, v47, v37
	v_exp_f32_e32 v33, v33
	v_div_fixup_f32 v115, v36, v34, v38
	v_fma_f32 v34, -v41, v44, 1.0
	v_fmac_f32_e32 v44, v34, v44
	v_div_scale_f32 v34, vcc, v29, v31, v29
	v_mul_f32_e32 v36, v34, v44
	v_fma_f32 v37, -v41, v36, v34
	s_waitcnt vmcnt(32)
	v_lshlrev_b32_e32 v32, 16, v32
	v_add_f32_e32 v33, 1.0, v33
	v_fmac_f32_e32 v36, v37, v44
	v_div_scale_f32 v37, s[0:1], v33, v33, v32
	v_rcp_f32_e32 v38, v37
	v_fma_f32 v34, -v41, v36, v34
	v_div_fmas_f32 v34, v34, v44, v36
	v_div_fixup_f32 v116, v34, v31, v29
	v_fma_f32 v29, -v37, v38, 1.0
	v_fmac_f32_e32 v38, v29, v38
	v_div_scale_f32 v29, vcc, v32, v33, v32
	v_mul_f32_e32 v31, v29, v38
	v_fma_f32 v34, -v37, v31, v29
	v_fmac_f32_e32 v31, v34, v38
	v_fma_f32 v29, -v37, v31, v29
	v_div_fmas_f32 v29, v29, v38, v31
	v_div_fixup_f32 v117, v29, v33, v32
	v_and_b32_e32 v114, 32, v2
	s_waitcnt vmcnt(20)
	v_fma_f32 v55, v28, v80, v13
	v_fmac_f32_e32 v55, v26, v79
	v_fma_f32 v54, v26, v80, v13
	v_fmac_f32_e32 v55, v27, v89
	v_fmac_f32_e32 v54, v27, v79
	v_fma_f32 v53, v27, v80, v13
	v_fmac_f32_e32 v55, v24, v78
	v_fmac_f32_e32 v54, v24, v89
	v_fmac_f32_e32 v53, v24, v79
	v_fma_f32 v52, v24, v80, v13
	v_fmac_f32_e32 v55, v25, v88
	v_fmac_f32_e32 v54, v25, v78
	v_fmac_f32_e32 v53, v25, v89
	v_fmac_f32_e32 v52, v25, v79
	v_fma_f32 v44, v25, v80, v13
	v_fmac_f32_e32 v55, v22, v87
	v_fmac_f32_e32 v54, v22, v88
	v_fmac_f32_e32 v53, v22, v78
	v_fmac_f32_e32 v52, v22, v89
	v_fmac_f32_e32 v44, v22, v79
	v_fma_f32 v47, v22, v80, v13
	v_fmac_f32_e32 v55, v23, v86
	v_fmac_f32_e32 v54, v23, v87
	v_fmac_f32_e32 v53, v23, v88
	v_fmac_f32_e32 v52, v23, v78
	v_fmac_f32_e32 v44, v23, v89
	v_fmac_f32_e32 v47, v23, v79
	v_fma_f32 v36, v23, v80, v13
	s_waitcnt vmcnt(11)
; __device__ __forceinline__ void conv_tile(const Params& p, int l, int item, const bf16* PROJ, bf16* CV, LAS float* sl) {
;     ...
;     for (int t = 0; t < 32; ++t) { float acc = bias;
; #pragma unroll
;         for (int j = 0; j < 31; ++j) acc = fmaf(u[t + j], w[j], acc);
;         y[t] = acc; y2[t] = acc * acc; }
	v_fmac_f32_e32 v55, v20, v112
	v_fmac_f32_e32 v54, v20, v86
	v_fmac_f32_e32 v53, v20, v87
	v_fmac_f32_e32 v52, v20, v88
	v_fmac_f32_e32 v44, v20, v78
	v_fmac_f32_e32 v47, v20, v89
	v_fmac_f32_e32 v36, v20, v79
	v_fma_f32 v37, v20, v80, v13
	v_fmac_f32_e32 v55, v21, v84
	v_fmac_f32_e32 v54, v21, v112
	v_fmac_f32_e32 v53, v21, v86
	v_fmac_f32_e32 v52, v21, v87
	v_fmac_f32_e32 v44, v21, v88
	v_fmac_f32_e32 v47, v21, v78
	v_fmac_f32_e32 v36, v21, v89
	v_fmac_f32_e32 v37, v21, v79
	v_fma_f32 v38, v21, v80, v13
	v_fmac_f32_e32 v55, v18, v83
	v_fmac_f32_e32 v54, v18, v84
	v_fmac_f32_e32 v53, v18, v112
	v_fmac_f32_e32 v52, v18, v86
	v_fmac_f32_e32 v44, v18, v87
	v_fmac_f32_e32 v47, v18, v88
	v_fmac_f32_e32 v36, v18, v78
	v_fmac_f32_e32 v37, v18, v89
	v_fmac_f32_e32 v38, v18, v79
	v_fma_f32 v41, v18, v80, v13
	v_fmac_f32_e32 v55, v19, v85
	v_fmac_f32_e32 v54, v19, v83
	v_fmac_f32_e32 v53, v19, v84
	v_fmac_f32_e32 v52, v19, v112
	v_fmac_f32_e32 v44, v19, v86
	v_fmac_f32_e32 v47, v19, v87
	v_fmac_f32_e32 v36, v19, v88
	v_fmac_f32_e32 v37, v19, v78
	v_fmac_f32_e32 v38, v19, v89
	v_fmac_f32_e32 v41, v19, v79
	v_fma_f32 v34, v19, v80, v13
	s_waitcnt vmcnt(10)
	v_fmac_f32_e32 v55, v16, v110
	v_fmac_f32_e32 v54, v16, v85
	v_fmac_f32_e32 v53, v16, v83
	v_fmac_f32_e32 v52, v16, v84
	v_fmac_f32_e32 v44, v16, v112
	v_fmac_f32_e32 v47, v16, v86
	v_fmac_f32_e32 v36, v16, v87
	v_fmac_f32_e32 v37, v16, v88
	v_fmac_f32_e32 v38, v16, v78
	v_fmac_f32_e32 v41, v16, v89
	v_fmac_f32_e32 v34, v16, v79
	v_fma_f32 v32, v16, v80, v13
	v_fmac_f32_e32 v55, v17, v82
	v_fmac_f32_e32 v54, v17, v110
	v_fmac_f32_e32 v53, v17, v85
	v_fmac_f32_e32 v52, v17, v83
	v_fmac_f32_e32 v44, v17, v84
	v_fmac_f32_e32 v47, v17, v112
	v_fmac_f32_e32 v36, v17, v86
	v_fmac_f32_e32 v37, v17, v87
	v_fmac_f32_e32 v38, v17, v88
	v_fmac_f32_e32 v41, v17, v78
	v_fmac_f32_e32 v34, v17, v89
	v_fmac_f32_e32 v32, v17, v79
	v_fma_f32 v31, v17, v80, v13
	v_fmac_f32_e32 v55, v14, v107
	v_fmac_f32_e32 v54, v14, v82
	v_fmac_f32_e32 v53, v14, v110
	v_fmac_f32_e32 v52, v14, v85
	v_fmac_f32_e32 v44, v14, v83
	v_fmac_f32_e32 v47, v14, v84
	v_fmac_f32_e32 v36, v14, v112
	v_fmac_f32_e32 v37, v14, v86
	v_fmac_f32_e32 v38, v14, v87
	v_fmac_f32_e32 v41, v14, v88
	v_fmac_f32_e32 v34, v14, v78
	v_fmac_f32_e32 v32, v14, v89
	v_fmac_f32_e32 v31, v14, v79
	v_fma_f32 v33, v14, v80, v13
	v_fmac_f32_e32 v55, v15, v105
	v_fmac_f32_e32 v54, v15, v107
	v_fmac_f32_e32 v53, v15, v82
	v_fmac_f32_e32 v52, v15, v110
	v_fmac_f32_e32 v44, v15, v85
	v_fmac_f32_e32 v47, v15, v83
	v_fmac_f32_e32 v36, v15, v84
	v_fmac_f32_e32 v37, v15, v112
	v_fmac_f32_e32 v38, v15, v86
	v_fmac_f32_e32 v41, v15, v87
	v_fmac_f32_e32 v34, v15, v88
	v_fmac_f32_e32 v32, v15, v78
	v_fmac_f32_e32 v31, v15, v89
	v_fmac_f32_e32 v33, v15, v79
	v_fma_f32 v29, v15, v80, v13
	s_waitcnt vmcnt(9)
	v_fmac_f32_e32 v55, v121, v109
	v_fmac_f32_e32 v54, v121, v105
	v_fmac_f32_e32 v53, v121, v107
	v_fmac_f32_e32 v52, v121, v82
	v_fmac_f32_e32 v44, v121, v110
	v_fmac_f32_e32 v47, v121, v85
	v_fmac_f32_e32 v36, v121, v83
	v_fmac_f32_e32 v37, v121, v84
	v_fmac_f32_e32 v38, v121, v112
	v_fmac_f32_e32 v41, v121, v86
	v_fmac_f32_e32 v34, v121, v87
	v_fmac_f32_e32 v32, v121, v88
	v_fmac_f32_e32 v31, v121, v78
	v_fmac_f32_e32 v33, v121, v89
	v_fmac_f32_e32 v29, v121, v79
	v_fma_f32 v28, v121, v80, v13
	v_fmac_f32_e32 v55, v119, v102
	v_fmac_f32_e32 v54, v119, v109
	v_fmac_f32_e32 v53, v119, v105
	v_fmac_f32_e32 v52, v119, v107
	v_fmac_f32_e32 v44, v119, v82
	v_fmac_f32_e32 v47, v119, v110
	v_fmac_f32_e32 v36, v119, v85
	v_fmac_f32_e32 v37, v119, v83
	v_fmac_f32_e32 v38, v119, v84
	v_fmac_f32_e32 v41, v119, v112
	v_fmac_f32_e32 v34, v119, v86
	v_fmac_f32_e32 v32, v119, v87
	v_fmac_f32_e32 v31, v119, v88
	v_fmac_f32_e32 v33, v119, v78
	v_fmac_f32_e32 v29, v119, v89
	v_fmac_f32_e32 v28, v119, v79
	v_fma_f32 v27, v119, v80, v13
	v_fmac_f32_e32 v55, v30, v101
	v_fmac_f32_e32 v54, v30, v102
	v_fmac_f32_e32 v53, v30, v109
	v_fmac_f32_e32 v52, v30, v105
	v_fmac_f32_e32 v44, v30, v107
	v_fmac_f32_e32 v47, v30, v82
	v_fmac_f32_e32 v36, v30, v110
	v_fmac_f32_e32 v37, v30, v85
	v_fmac_f32_e32 v38, v30, v83
	v_fmac_f32_e32 v41, v30, v84
	v_fmac_f32_e32 v34, v30, v112
	v_fmac_f32_e32 v32, v30, v86
	v_fmac_f32_e32 v31, v30, v87
	v_fmac_f32_e32 v33, v30, v88
	v_fmac_f32_e32 v29, v30, v78
	v_fmac_f32_e32 v28, v30, v89
	v_fmac_f32_e32 v27, v30, v79
	v_fma_f32 v30, v30, v80, v13
	v_fmac_f32_e32 v30, v111, v79
	v_fma_f32 v25, v111, v80, v13
	v_fma_f32 v24, v91, v80, v13
	v_fmac_f32_e32 v30, v91, v89
	v_fmac_f32_e32 v25, v91, v79
	v_fmac_f32_e32 v24, v90, v79
	v_fma_f32 v23, v90, v80, v13
	v_fmac_f32_e32 v30, v90, v78
	v_fmac_f32_e32 v25, v90, v89
	v_fmac_f32_e32 v24, v81, v89
	v_fmac_f32_e32 v23, v81, v79
	v_fma_f32 v26, v81, v80, v13
	v_fma_f32 v22, v71, v80, v13
	v_fmac_f32_e32 v30, v81, v88
	v_fmac_f32_e32 v25, v81, v78
	v_fmac_f32_e32 v24, v77, v78
	v_fmac_f32_e32 v23, v77, v89
	v_fmac_f32_e32 v26, v77, v79
	v_fma_f32 v21, v77, v80, v13
	v_fmac_f32_e32 v22, v69, v79
	v_fma_f32 v17, v69, v80, v13
	v_fma_f32 v18, v61, v80, v13
	v_fmac_f32_e32 v30, v77, v87
	v_fmac_f32_e32 v25, v77, v88
	v_fmac_f32_e32 v24, v76, v88
	v_fmac_f32_e32 v23, v76, v78
	v_fmac_f32_e32 v26, v76, v89
	v_fmac_f32_e32 v21, v76, v79
	v_fma_f32 v20, v76, v80, v13
	v_fma_f32 v19, v74, v80, v13
	v_fmac_f32_e32 v22, v66, v89
	v_fmac_f32_e32 v17, v66, v79
	v_fma_f32 v16, v66, v80, v13
	v_fma_f32 v15, v63, v80, v13
	v_fmac_f32_e32 v18, v58, v79
	v_fma_f32 v14, v58, v80, v13
	v_fmac_f32_e32 v13, v56, v80
	v_fmac_f32_e32 v30, v76, v86
	v_fmac_f32_e32 v25, v76, v87
	v_fmac_f32_e32 v24, v74, v87
	v_fmac_f32_e32 v23, v74, v88
; __device__ __forceinline__ void conv_tile(const Params& p, int l, int item, const bf16* PROJ, bf16* CV, LAS float* sl) {
;     ...
;     for (int t = 0; t < 32; ++t) { float acc = bias;
; #pragma unroll
;         for (int j = 0; j < 31; ++j) acc = fmaf(u[t + j], w[j], acc);
;         y[t] = acc; y2[t] = acc * acc; }
	v_fmac_f32_e32 v26, v74, v78
	v_fmac_f32_e32 v21, v74, v89
	v_fmac_f32_e32 v20, v74, v79
	v_fmac_f32_e32 v22, v63, v78
	v_fmac_f32_e32 v17, v63, v89
	v_fmac_f32_e32 v16, v63, v79
	v_fmac_f32_e32 v18, v56, v89
	v_fmac_f32_e32 v14, v56, v79
	v_fmac_f32_e32 v13, v57, v79
	v_fmac_f32_e32 v30, v74, v112
	v_fmac_f32_e32 v25, v74, v86
	v_fmac_f32_e32 v24, v71, v86
	v_fmac_f32_e32 v23, v71, v87
	v_fmac_f32_e32 v26, v71, v88
	v_fmac_f32_e32 v21, v71, v78
	v_fmac_f32_e32 v20, v71, v89
	v_fmac_f32_e32 v19, v71, v79
	v_fmac_f32_e32 v22, v61, v88
	v_fmac_f32_e32 v17, v61, v78
	v_fmac_f32_e32 v16, v61, v89
	v_fmac_f32_e32 v15, v61, v79
	v_fmac_f32_e32 v18, v57, v78
	v_fmac_f32_e32 v14, v57, v89
	v_fmac_f32_e32 v13, v59, v89
	v_fmac_f32_e32 v30, v71, v84
	v_fmac_f32_e32 v25, v71, v112
	v_fmac_f32_e32 v24, v69, v112
	v_fmac_f32_e32 v23, v69, v86
	v_fmac_f32_e32 v26, v69, v87
	v_fmac_f32_e32 v21, v69, v88
	v_fmac_f32_e32 v20, v69, v78
	v_fmac_f32_e32 v19, v69, v89
	v_fmac_f32_e32 v22, v58, v87
	v_fmac_f32_e32 v17, v58, v88
	v_fmac_f32_e32 v16, v58, v78
	v_fmac_f32_e32 v15, v58, v89
	v_fmac_f32_e32 v18, v59, v88
	v_fmac_f32_e32 v14, v59, v78
	v_fmac_f32_e32 v13, v60, v78
	v_fmac_f32_e32 v30, v69, v83
	v_fmac_f32_e32 v25, v69, v84
	v_fmac_f32_e32 v24, v66, v84
	v_fmac_f32_e32 v23, v66, v112
	v_fmac_f32_e32 v26, v66, v86
	v_fmac_f32_e32 v21, v66, v87
	v_fmac_f32_e32 v20, v66, v88
	v_fmac_f32_e32 v19, v66, v78
	v_fmac_f32_e32 v22, v56, v86
	v_fmac_f32_e32 v17, v56, v87
	v_fmac_f32_e32 v16, v56, v88
	v_fmac_f32_e32 v15, v56, v78
	v_fmac_f32_e32 v18, v60, v87
	v_fmac_f32_e32 v14, v60, v88
	v_fmac_f32_e32 v13, v62, v88
	v_fmac_f32_e32 v30, v66, v85
	v_fmac_f32_e32 v25, v66, v83
	v_fmac_f32_e32 v24, v63, v83
	v_fmac_f32_e32 v23, v63, v84
	v_fmac_f32_e32 v26, v63, v112
	v_fmac_f32_e32 v21, v63, v86
	v_fmac_f32_e32 v20, v63, v87
	v_fmac_f32_e32 v19, v63, v88
	v_fmac_f32_e32 v22, v57, v112
	v_fmac_f32_e32 v17, v57, v86
	v_fmac_f32_e32 v16, v57, v87
	v_fmac_f32_e32 v15, v57, v88
	v_fmac_f32_e32 v18, v62, v86
	v_fmac_f32_e32 v14, v62, v87
	v_fmac_f32_e32 v13, v64, v87
	v_fmac_f32_e32 v30, v63, v110
	v_fmac_f32_e32 v25, v63, v85
	v_fmac_f32_e32 v24, v61, v85
	v_fmac_f32_e32 v23, v61, v83
	v_fmac_f32_e32 v26, v61, v84
	v_fmac_f32_e32 v21, v61, v112
	v_fmac_f32_e32 v20, v61, v86
	v_fmac_f32_e32 v19, v61, v87
	v_fmac_f32_e32 v22, v59, v84
	v_fmac_f32_e32 v17, v59, v112
	v_fmac_f32_e32 v16, v59, v86
	v_fmac_f32_e32 v15, v59, v87
	v_fmac_f32_e32 v18, v64, v112
	v_fmac_f32_e32 v14, v64, v86
	v_fmac_f32_e32 v13, v65, v86
	v_fmac_f32_e32 v30, v61, v82
	v_fmac_f32_e32 v25, v61, v110
	v_fmac_f32_e32 v24, v58, v110
	v_fmac_f32_e32 v23, v58, v85
	v_fmac_f32_e32 v26, v58, v83
	v_fmac_f32_e32 v21, v58, v84
	v_fmac_f32_e32 v20, v58, v112
	v_fmac_f32_e32 v19, v58, v86
	v_fmac_f32_e32 v22, v60, v83
	v_fmac_f32_e32 v17, v60, v84
	v_fmac_f32_e32 v16, v60, v112
	v_fmac_f32_e32 v15, v60, v86
	v_fmac_f32_e32 v18, v65, v84
	v_fmac_f32_e32 v14, v65, v112
	v_fmac_f32_e32 v13, v67, v112
	v_fmac_f32_e32 v30, v58, v107
	v_fmac_f32_e32 v25, v58, v82
	v_fmac_f32_e32 v24, v56, v82
	v_fmac_f32_e32 v23, v56, v110
	v_fmac_f32_e32 v26, v56, v85
	v_fmac_f32_e32 v21, v56, v83
	v_fmac_f32_e32 v20, v56, v84
	v_fmac_f32_e32 v19, v56, v112
	v_fmac_f32_e32 v22, v62, v85
	v_fmac_f32_e32 v17, v62, v83
	v_fmac_f32_e32 v16, v62, v84
	v_fmac_f32_e32 v15, v62, v112
	v_fmac_f32_e32 v18, v67, v83
	v_fmac_f32_e32 v14, v67, v84
	v_fmac_f32_e32 v13, v68, v84
	v_fmac_f32_e32 v30, v56, v105
	v_fmac_f32_e32 v25, v56, v107
	v_fmac_f32_e32 v24, v57, v107
	v_fmac_f32_e32 v23, v57, v82
	v_fmac_f32_e32 v26, v57, v110
	v_fmac_f32_e32 v21, v57, v85
	v_fmac_f32_e32 v20, v57, v83
	v_fmac_f32_e32 v19, v57, v84
	v_fmac_f32_e32 v22, v64, v110
	v_fmac_f32_e32 v17, v64, v85
	v_fmac_f32_e32 v16, v64, v83
	v_fmac_f32_e32 v15, v64, v84
	v_fmac_f32_e32 v18, v68, v85
	v_fmac_f32_e32 v14, v68, v83
	v_fmac_f32_e32 v13, v70, v83
	v_fmac_f32_e32 v30, v57, v109
	v_fmac_f32_e32 v25, v57, v105
	v_fmac_f32_e32 v24, v59, v105
	v_fmac_f32_e32 v23, v59, v107
	v_fmac_f32_e32 v26, v59, v82
	v_fmac_f32_e32 v21, v59, v110
	v_fmac_f32_e32 v20, v59, v85
	v_fmac_f32_e32 v19, v59, v83
	v_fmac_f32_e32 v22, v65, v82
	v_fmac_f32_e32 v17, v65, v110
	v_fmac_f32_e32 v16, v65, v85
	v_fmac_f32_e32 v15, v65, v83
	v_fmac_f32_e32 v18, v70, v110
	v_fmac_f32_e32 v14, v70, v85
	v_fmac_f32_e32 v13, v72, v85
	v_fmac_f32_e32 v27, v111, v89
	v_fmac_f32_e32 v30, v59, v102
	v_fmac_f32_e32 v25, v59, v109
	v_fmac_f32_e32 v24, v60, v109
	v_fmac_f32_e32 v23, v60, v105
	v_fmac_f32_e32 v26, v60, v107
	v_fmac_f32_e32 v21, v60, v82
	v_fmac_f32_e32 v20, v60, v110
	v_fmac_f32_e32 v19, v60, v85
	v_fmac_f32_e32 v22, v67, v107
	v_fmac_f32_e32 v17, v67, v82
	v_fmac_f32_e32 v16, v67, v110
	v_fmac_f32_e32 v15, v67, v85
	v_fmac_f32_e32 v18, v72, v82
	v_fmac_f32_e32 v14, v72, v110
	v_fmac_f32_e32 v13, v73, v110
	v_fmac_f32_e32 v54, v111, v101
	v_fmac_f32_e32 v53, v111, v102
	v_fmac_f32_e32 v52, v111, v109
	v_fmac_f32_e32 v44, v111, v105
	v_fmac_f32_e32 v47, v111, v107
	v_fmac_f32_e32 v36, v111, v82
	v_fmac_f32_e32 v37, v111, v110
	v_fmac_f32_e32 v38, v111, v85
	v_fmac_f32_e32 v41, v111, v83
	v_fmac_f32_e32 v34, v111, v84
	v_fmac_f32_e32 v32, v111, v112
	v_fmac_f32_e32 v31, v111, v86
	v_fmac_f32_e32 v33, v111, v87
	v_fmac_f32_e32 v29, v111, v88
	v_fmac_f32_e32 v28, v111, v78
	v_fmac_f32_e32 v27, v91, v78
	v_fmac_f32_e32 v30, v60, v101
	v_fmac_f32_e32 v25, v60, v102
	v_fmac_f32_e32 v24, v62, v102
	v_fmac_f32_e32 v23, v62, v109
	v_fmac_f32_e32 v26, v62, v105
	v_fmac_f32_e32 v21, v62, v107
	v_fmac_f32_e32 v20, v62, v82
	v_fmac_f32_e32 v19, v62, v110
	v_fmac_f32_e32 v22, v68, v105
	v_fmac_f32_e32 v17, v68, v107
	v_fmac_f32_e32 v16, v68, v82
	v_fmac_f32_e32 v15, v68, v110
	v_fmac_f32_e32 v18, v73, v107
	v_fmac_f32_e32 v14, v73, v82
	v_fmac_f32_e32 v13, v75, v82
	v_fmac_f32_e32 v54, v91, v98
	v_fmac_f32_e32 v53, v91, v101
	v_fmac_f32_e32 v52, v91, v102
	v_fmac_f32_e32 v44, v91, v109
	v_fmac_f32_e32 v47, v91, v105
	v_fmac_f32_e32 v36, v91, v107
	v_fmac_f32_e32 v37, v91, v82
	v_fmac_f32_e32 v38, v91, v110
	v_fmac_f32_e32 v41, v91, v85
	v_fmac_f32_e32 v34, v91, v83
	v_fmac_f32_e32 v32, v91, v84
	v_fmac_f32_e32 v31, v91, v112
	v_fmac_f32_e32 v33, v91, v86
	v_fmac_f32_e32 v29, v91, v87
	v_fmac_f32_e32 v28, v91, v88
	v_fmac_f32_e32 v27, v90, v88
	v_fmac_f32_e32 v30, v62, v98
	v_fmac_f32_e32 v25, v62, v101
	v_fmac_f32_e32 v24, v64, v101
	v_fmac_f32_e32 v23, v64, v102
	v_fmac_f32_e32 v26, v64, v109
	v_fmac_f32_e32 v21, v64, v105
	v_fmac_f32_e32 v20, v64, v107
	v_fmac_f32_e32 v19, v64, v82
	v_fmac_f32_e32 v22, v70, v109
	v_fmac_f32_e32 v17, v70, v105
	v_fmac_f32_e32 v16, v70, v107
	v_fmac_f32_e32 v15, v70, v82
	v_fmac_f32_e32 v18, v75, v105
	v_fmac_f32_e32 v14, v75, v107
	v_fmac_f32_e32 v13, v115, v107
	s_waitcnt vmcnt(8)
; __device__ __forceinline__ void conv_tile(const Params& p, int l, int item, const bf16* PROJ, bf16* CV, LAS float* sl) {
;     ...
;     for (int t = 0; t < 32; ++t) { float acc = bias;
; #pragma unroll
;         for (int j = 0; j < 31; ++j) acc = fmaf(u[t + j], w[j], acc);
;         y[t] = acc; y2[t] = acc * acc; }
	v_fmac_f32_e32 v54, v90, v108
	v_fmac_f32_e32 v53, v90, v98
	v_fmac_f32_e32 v52, v90, v101
	v_fmac_f32_e32 v44, v90, v102
	v_fmac_f32_e32 v47, v90, v109
	v_fmac_f32_e32 v36, v90, v105
	v_fmac_f32_e32 v37, v90, v107
	v_fmac_f32_e32 v38, v90, v82
	v_fmac_f32_e32 v41, v90, v110
	v_fmac_f32_e32 v34, v90, v85
	v_fmac_f32_e32 v32, v90, v83
	v_fmac_f32_e32 v31, v90, v84
	v_fmac_f32_e32 v33, v90, v112
	v_fmac_f32_e32 v29, v90, v86
	v_fmac_f32_e32 v28, v90, v87
	v_fmac_f32_e32 v27, v81, v87
	v_fmac_f32_e32 v30, v64, v108
	v_fmac_f32_e32 v25, v64, v98
	v_fmac_f32_e32 v24, v65, v98
	v_fmac_f32_e32 v23, v65, v101
	v_fmac_f32_e32 v26, v65, v102
	v_fmac_f32_e32 v21, v65, v109
	v_fmac_f32_e32 v20, v65, v105
	v_fmac_f32_e32 v19, v65, v107
	v_fmac_f32_e32 v22, v72, v102
	v_fmac_f32_e32 v17, v72, v109
	v_fmac_f32_e32 v16, v72, v105
	v_fmac_f32_e32 v15, v72, v107
	v_fmac_f32_e32 v18, v115, v109
	v_fmac_f32_e32 v14, v115, v105
	v_fmac_f32_e32 v13, v116, v105
	v_fmac_f32_e32 v54, v81, v94
	v_fmac_f32_e32 v53, v81, v108
	v_fmac_f32_e32 v52, v81, v98
	v_fmac_f32_e32 v44, v81, v101
	v_fmac_f32_e32 v47, v81, v102
	v_fmac_f32_e32 v36, v81, v109
	v_fmac_f32_e32 v37, v81, v105
	v_fmac_f32_e32 v38, v81, v107
	v_fmac_f32_e32 v41, v81, v82
	v_fmac_f32_e32 v34, v81, v110
	v_fmac_f32_e32 v32, v81, v85
	v_fmac_f32_e32 v31, v81, v83
	v_fmac_f32_e32 v33, v81, v84
	v_fmac_f32_e32 v29, v81, v112
	v_fmac_f32_e32 v28, v81, v86
	v_fmac_f32_e32 v27, v77, v86
	v_fmac_f32_e32 v30, v65, v94
	v_fmac_f32_e32 v25, v65, v108
	v_fmac_f32_e32 v24, v67, v108
	v_fmac_f32_e32 v23, v67, v98
	v_fmac_f32_e32 v26, v67, v101
	v_fmac_f32_e32 v21, v67, v102
	v_fmac_f32_e32 v20, v67, v109
	v_fmac_f32_e32 v19, v67, v105
	v_fmac_f32_e32 v22, v73, v101
	v_fmac_f32_e32 v17, v73, v102
	v_fmac_f32_e32 v16, v73, v109
	v_fmac_f32_e32 v15, v73, v105
	v_fmac_f32_e32 v18, v116, v102
	v_fmac_f32_e32 v14, v116, v109
	v_fmac_f32_e32 v13, v117, v109
	v_fmac_f32_e32 v54, v77, v93
	v_fmac_f32_e32 v53, v77, v94
	v_fmac_f32_e32 v52, v77, v108
	v_fmac_f32_e32 v44, v77, v98
	v_fmac_f32_e32 v47, v77, v101
	v_fmac_f32_e32 v36, v77, v102
	v_fmac_f32_e32 v37, v77, v109
	v_fmac_f32_e32 v38, v77, v105
	v_fmac_f32_e32 v41, v77, v107
	v_fmac_f32_e32 v34, v77, v82
	v_fmac_f32_e32 v32, v77, v110
	v_fmac_f32_e32 v31, v77, v85
	v_fmac_f32_e32 v33, v77, v83
	v_fmac_f32_e32 v29, v77, v84
	v_fmac_f32_e32 v28, v77, v112
	v_fmac_f32_e32 v27, v76, v112
	v_fmac_f32_e32 v30, v67, v93
	v_fmac_f32_e32 v25, v67, v94
	v_fmac_f32_e32 v24, v68, v94
	v_fmac_f32_e32 v23, v68, v108
	v_fmac_f32_e32 v26, v68, v98
	v_fmac_f32_e32 v21, v68, v101
	v_fmac_f32_e32 v20, v68, v102
	v_fmac_f32_e32 v19, v68, v109
	v_fmac_f32_e32 v22, v75, v98
	v_fmac_f32_e32 v17, v75, v101
	v_fmac_f32_e32 v16, v75, v102
	v_fmac_f32_e32 v15, v75, v109
	v_fmac_f32_e32 v18, v117, v101
	v_fmac_f32_e32 v14, v117, v102
	v_fmac_f32_e32 v13, v6, v102
	v_fmac_f32_e32 v54, v76, v92
	v_fmac_f32_e32 v53, v76, v93
	v_fmac_f32_e32 v52, v76, v94
	v_fmac_f32_e32 v44, v76, v108
	v_fmac_f32_e32 v47, v76, v98
	v_fmac_f32_e32 v36, v76, v101
	v_fmac_f32_e32 v37, v76, v102
	v_fmac_f32_e32 v38, v76, v109
	v_fmac_f32_e32 v41, v76, v105
	v_fmac_f32_e32 v34, v76, v107
	v_fmac_f32_e32 v32, v76, v82
	v_fmac_f32_e32 v31, v76, v110
	v_fmac_f32_e32 v33, v76, v85
	v_fmac_f32_e32 v29, v76, v83
	v_fmac_f32_e32 v28, v76, v84
	v_fmac_f32_e32 v27, v74, v84
	v_fmac_f32_e32 v30, v68, v92
	v_fmac_f32_e32 v25, v68, v93
	v_fmac_f32_e32 v24, v70, v93
	v_fmac_f32_e32 v23, v70, v94
	v_fmac_f32_e32 v26, v70, v108
	v_fmac_f32_e32 v21, v70, v98
	v_fmac_f32_e32 v20, v70, v101
	v_fmac_f32_e32 v19, v70, v102
	v_fmac_f32_e32 v22, v115, v108
	v_fmac_f32_e32 v17, v115, v98
	v_fmac_f32_e32 v16, v115, v101
	v_fmac_f32_e32 v15, v115, v102
	v_fmac_f32_e32 v18, v6, v98
	v_fmac_f32_e32 v14, v6, v101
	v_fmac_f32_e32 v13, v8, v101
	s_waitcnt vmcnt(7)
	v_fmac_f32_e32 v54, v74, v96
	v_fmac_f32_e32 v53, v74, v92
	v_fmac_f32_e32 v52, v74, v93
	v_fmac_f32_e32 v44, v74, v94
	v_fmac_f32_e32 v47, v74, v108
	v_fmac_f32_e32 v36, v74, v98
	v_fmac_f32_e32 v37, v74, v101
	v_fmac_f32_e32 v38, v74, v102
	v_fmac_f32_e32 v41, v74, v109
	v_fmac_f32_e32 v34, v74, v105
	v_fmac_f32_e32 v32, v74, v107
	v_fmac_f32_e32 v31, v74, v82
	v_fmac_f32_e32 v33, v74, v110
	v_fmac_f32_e32 v29, v74, v85
	v_fmac_f32_e32 v28, v74, v83
	v_fmac_f32_e32 v27, v71, v83
	v_fmac_f32_e32 v30, v70, v96
	v_fmac_f32_e32 v25, v70, v92
	v_fmac_f32_e32 v24, v72, v92
	v_fmac_f32_e32 v23, v72, v93
	v_fmac_f32_e32 v26, v72, v94
	v_fmac_f32_e32 v21, v72, v108
	v_fmac_f32_e32 v20, v72, v98
	v_fmac_f32_e32 v19, v72, v101
	v_fmac_f32_e32 v22, v116, v94
	v_fmac_f32_e32 v17, v116, v108
	v_fmac_f32_e32 v16, v116, v98
	v_fmac_f32_e32 v15, v116, v101
	v_fmac_f32_e32 v18, v8, v108
	v_fmac_f32_e32 v14, v8, v98
	v_fmac_f32_e32 v13, v7, v98
	s_waitcnt vmcnt(5)
	v_fmac_f32_e32 v54, v71, v106
	v_fmac_f32_e32 v53, v71, v96
	v_fmac_f32_e32 v52, v71, v92
	v_fmac_f32_e32 v44, v71, v93
	v_fmac_f32_e32 v47, v71, v94
	v_fmac_f32_e32 v36, v71, v108
	v_fmac_f32_e32 v37, v71, v98
	v_fmac_f32_e32 v38, v71, v101
	v_fmac_f32_e32 v41, v71, v102
	v_fmac_f32_e32 v34, v71, v109
	v_fmac_f32_e32 v32, v71, v105
	v_fmac_f32_e32 v31, v71, v107
	v_fmac_f32_e32 v33, v71, v82
	v_fmac_f32_e32 v29, v71, v110
	v_fmac_f32_e32 v28, v71, v85
	v_fmac_f32_e32 v27, v69, v85
	v_fmac_f32_e32 v30, v72, v106
	v_fmac_f32_e32 v25, v72, v96
	v_fmac_f32_e32 v24, v73, v96
	v_fmac_f32_e32 v23, v73, v92
	v_fmac_f32_e32 v26, v73, v93
	v_fmac_f32_e32 v21, v73, v94
	v_fmac_f32_e32 v20, v73, v108
	v_fmac_f32_e32 v19, v73, v98
	v_fmac_f32_e32 v22, v117, v93
	v_fmac_f32_e32 v17, v117, v94
	v_fmac_f32_e32 v16, v117, v108
	v_fmac_f32_e32 v15, v117, v98
	v_fmac_f32_e32 v18, v7, v94
	v_fmac_f32_e32 v14, v7, v108
	v_fmac_f32_e32 v13, v35, v108
	v_fmac_f32_e32 v55, v111, v98
	s_waitcnt vmcnt(4)
; __device__ __forceinline__ void conv_tile(const Params& p, int l, int item, const bf16* PROJ, bf16* CV, LAS float* sl) {
;     ...
;     for (int t = 0; t < 32; ++t) { float acc = bias;
; #pragma unroll
;         for (int j = 0; j < 31; ++j) acc = fmaf(u[t + j], w[j], acc);
;         y[t] = acc; y2[t] = acc * acc; }
	v_fmac_f32_e32 v54, v69, v104
	v_fmac_f32_e32 v53, v69, v106
	v_fmac_f32_e32 v52, v69, v96
	v_fmac_f32_e32 v44, v69, v92
	v_fmac_f32_e32 v47, v69, v93
	v_fmac_f32_e32 v36, v69, v94
	v_fmac_f32_e32 v37, v69, v108
	v_fmac_f32_e32 v38, v69, v98
	v_fmac_f32_e32 v41, v69, v101
	v_fmac_f32_e32 v34, v69, v102
	v_fmac_f32_e32 v32, v69, v109
	v_fmac_f32_e32 v31, v69, v105
	v_fmac_f32_e32 v33, v69, v107
	v_fmac_f32_e32 v29, v69, v82
	v_fmac_f32_e32 v28, v69, v110
	v_fmac_f32_e32 v27, v66, v110
	v_fmac_f32_e32 v30, v73, v104
	v_fmac_f32_e32 v25, v73, v106
	v_fmac_f32_e32 v24, v75, v106
	v_fmac_f32_e32 v23, v75, v96
	v_fmac_f32_e32 v26, v75, v92
	v_fmac_f32_e32 v21, v75, v93
	v_fmac_f32_e32 v20, v75, v94
	v_fmac_f32_e32 v19, v75, v108
	v_fmac_f32_e32 v22, v6, v92
	v_fmac_f32_e32 v17, v6, v93
	v_fmac_f32_e32 v16, v6, v94
	v_fmac_f32_e32 v15, v6, v108
	v_fmac_f32_e32 v18, v35, v93
	v_fmac_f32_e32 v14, v35, v94
	v_fmac_f32_e32 v13, v9, v94
	v_fmac_f32_e32 v55, v91, v108
	s_waitcnt vmcnt(3)
	v_fmac_f32_e32 v54, v66, v103
	v_fmac_f32_e32 v53, v66, v104
	v_fmac_f32_e32 v52, v66, v106
	v_fmac_f32_e32 v44, v66, v96
	v_fmac_f32_e32 v47, v66, v92
	v_fmac_f32_e32 v36, v66, v93
	v_fmac_f32_e32 v37, v66, v94
	v_fmac_f32_e32 v38, v66, v108
	v_fmac_f32_e32 v41, v66, v98
	v_fmac_f32_e32 v34, v66, v101
	v_fmac_f32_e32 v32, v66, v102
	v_fmac_f32_e32 v31, v66, v109
	v_fmac_f32_e32 v33, v66, v105
	v_fmac_f32_e32 v29, v66, v107
	v_fmac_f32_e32 v28, v66, v82
	v_fmac_f32_e32 v27, v63, v82
	v_fmac_f32_e32 v30, v75, v103
	v_fmac_f32_e32 v25, v75, v104
	v_fmac_f32_e32 v24, v115, v104
	v_fmac_f32_e32 v23, v115, v106
	v_fmac_f32_e32 v26, v115, v96
	v_fmac_f32_e32 v21, v115, v92
	v_fmac_f32_e32 v20, v115, v93
	v_fmac_f32_e32 v19, v115, v94
	v_fmac_f32_e32 v22, v8, v96
	v_fmac_f32_e32 v17, v8, v92
	v_fmac_f32_e32 v16, v8, v93
	v_fmac_f32_e32 v15, v8, v94
	v_fmac_f32_e32 v18, v9, v92
	v_fmac_f32_e32 v14, v9, v93
	v_fmac_f32_e32 v13, v40, v93
	v_fmac_f32_e32 v55, v90, v94
	v_fmac_f32_e32 v54, v63, v95
	v_fmac_f32_e32 v53, v63, v103
	v_fmac_f32_e32 v52, v63, v104
	v_fmac_f32_e32 v44, v63, v106
	v_fmac_f32_e32 v47, v63, v96
	v_fmac_f32_e32 v36, v63, v92
	v_fmac_f32_e32 v37, v63, v93
	v_fmac_f32_e32 v38, v63, v94
	v_fmac_f32_e32 v41, v63, v108
	v_fmac_f32_e32 v34, v63, v98
	v_fmac_f32_e32 v32, v63, v101
	v_fmac_f32_e32 v31, v63, v102
	v_fmac_f32_e32 v33, v63, v109
	v_fmac_f32_e32 v29, v63, v105
	v_fmac_f32_e32 v28, v63, v107
	v_fmac_f32_e32 v27, v61, v107
	v_fmac_f32_e32 v30, v115, v95
	v_fmac_f32_e32 v25, v115, v103
	v_fmac_f32_e32 v24, v116, v103
	v_fmac_f32_e32 v23, v116, v104
	v_fmac_f32_e32 v26, v116, v106
	v_fmac_f32_e32 v21, v116, v96
	v_fmac_f32_e32 v20, v116, v92
	v_fmac_f32_e32 v19, v116, v93
	v_fmac_f32_e32 v22, v7, v106
	v_fmac_f32_e32 v17, v7, v96
	v_fmac_f32_e32 v16, v7, v92
	v_fmac_f32_e32 v15, v7, v93
	v_fmac_f32_e32 v18, v40, v96
	v_fmac_f32_e32 v14, v40, v92
	v_fmac_f32_e32 v13, v39, v92
	v_fmac_f32_e32 v55, v81, v93
	s_waitcnt vmcnt(2)
	v_fmac_f32_e32 v54, v61, v99
	v_fmac_f32_e32 v53, v61, v95
	v_fmac_f32_e32 v52, v61, v103
	v_fmac_f32_e32 v44, v61, v104
	v_fmac_f32_e32 v47, v61, v106
	v_fmac_f32_e32 v36, v61, v96
	v_fmac_f32_e32 v37, v61, v92
	v_fmac_f32_e32 v38, v61, v93
	v_fmac_f32_e32 v41, v61, v94
	v_fmac_f32_e32 v34, v61, v108
	v_fmac_f32_e32 v32, v61, v98
	v_fmac_f32_e32 v31, v61, v101
	v_fmac_f32_e32 v33, v61, v102
	v_fmac_f32_e32 v29, v61, v109
	v_fmac_f32_e32 v28, v61, v105
	v_fmac_f32_e32 v27, v58, v105
	v_fmac_f32_e32 v30, v116, v99
	v_fmac_f32_e32 v25, v116, v95
	v_fmac_f32_e32 v24, v117, v95
	v_fmac_f32_e32 v23, v117, v103
	v_fmac_f32_e32 v26, v117, v104
	v_fmac_f32_e32 v21, v117, v106
	v_fmac_f32_e32 v20, v117, v96
	v_fmac_f32_e32 v19, v117, v92
	v_fmac_f32_e32 v22, v35, v104
	v_fmac_f32_e32 v17, v35, v106
	v_fmac_f32_e32 v16, v35, v96
	v_fmac_f32_e32 v15, v35, v92
	v_fmac_f32_e32 v18, v39, v106
	v_fmac_f32_e32 v14, v39, v96
	v_fmac_f32_e32 v13, v43, v96
	v_fmac_f32_e32 v55, v77, v92
	s_waitcnt vmcnt(1)
	v_fmac_f32_e32 v54, v58, v97
	v_fmac_f32_e32 v53, v58, v99
	v_fmac_f32_e32 v52, v58, v95
	v_fmac_f32_e32 v44, v58, v103
	v_fmac_f32_e32 v47, v58, v104
	v_fmac_f32_e32 v36, v58, v106
	v_fmac_f32_e32 v37, v58, v96
	v_fmac_f32_e32 v38, v58, v92
	v_fmac_f32_e32 v41, v58, v93
	v_fmac_f32_e32 v34, v58, v94
	v_fmac_f32_e32 v32, v58, v108
	v_fmac_f32_e32 v31, v58, v98
	v_fmac_f32_e32 v33, v58, v101
	v_fmac_f32_e32 v29, v58, v102
	v_fmac_f32_e32 v28, v58, v109
	v_fmac_f32_e32 v27, v56, v109
	v_fmac_f32_e32 v30, v117, v97
	v_fmac_f32_e32 v25, v117, v99
	v_fmac_f32_e32 v24, v6, v99
	v_fmac_f32_e32 v23, v6, v95
	v_fmac_f32_e32 v26, v6, v103
	v_fmac_f32_e32 v21, v6, v104
	v_fmac_f32_e32 v20, v6, v106
	v_fmac_f32_e32 v19, v6, v96
	v_fmac_f32_e32 v22, v9, v103
	v_fmac_f32_e32 v17, v9, v104
	v_fmac_f32_e32 v16, v9, v106
	v_fmac_f32_e32 v15, v9, v96
	v_fmac_f32_e32 v18, v43, v104
	v_fmac_f32_e32 v14, v43, v106
	v_fmac_f32_e32 v13, v42, v106
	v_fmac_f32_e32 v55, v76, v96
	s_waitcnt vmcnt(0)
; __device__ __forceinline__ float wave_reduce32(const float (&v)[32], int lane) {
;     float a[16], b[8], c[4], d[2], e;
;     { const bool h = lane & 32;
; #pragma unroll
;       for (int t = 0; t < 16; ++t) { const float keep = h ? v[t + 16] : v[t], send = h ? v[t] : v[t + 16]; a[t] = keep + __shfl_xor(send, 32); } }
; __device__ __forceinline__ void conv_tile(const Params& p, int l, int item, const bf16* PROJ, bf16* CV, LAS float* sl) {
;     ...
;     for (int t = 0; t < 32; ++t) { float acc = bias;
; #pragma unroll
;         for (int j = 0; j < 31; ++j) acc = fmaf(u[t + j], w[j], acc);
;         y[t] = acc; y2[t] = acc * acc; }
;     const float r1 = wave_reduce32(y, lane), r2 = wave_reduce32(y2, lane);
	v_fmac_f32_e32 v54, v56, v100
	v_fmac_f32_e32 v53, v56, v97
	v_fmac_f32_e32 v52, v56, v99
	v_fmac_f32_e32 v44, v56, v95
	v_fmac_f32_e32 v47, v56, v103
	v_fmac_f32_e32 v36, v56, v104
	v_fmac_f32_e32 v37, v56, v106
	v_fmac_f32_e32 v38, v56, v96
	v_fmac_f32_e32 v41, v56, v92
	v_fmac_f32_e32 v34, v56, v93
	v_fmac_f32_e32 v32, v56, v94
	v_fmac_f32_e32 v31, v56, v108
	v_fmac_f32_e32 v33, v56, v98
	v_fmac_f32_e32 v29, v56, v101
	v_fmac_f32_e32 v28, v56, v102
	v_fmac_f32_e32 v27, v57, v102
	v_fmac_f32_e32 v30, v6, v100
	v_fmac_f32_e32 v25, v6, v97
	v_fmac_f32_e32 v24, v8, v97
	v_fmac_f32_e32 v23, v8, v99
	v_fmac_f32_e32 v26, v8, v95
	v_fmac_f32_e32 v21, v8, v103
	v_fmac_f32_e32 v20, v8, v104
	v_fmac_f32_e32 v19, v8, v106
	v_fmac_f32_e32 v22, v40, v95
	v_fmac_f32_e32 v17, v40, v103
	v_fmac_f32_e32 v16, v40, v104
	v_fmac_f32_e32 v15, v40, v106
	v_fmac_f32_e32 v18, v42, v103
	v_fmac_f32_e32 v14, v42, v104
	v_fmac_f32_e32 v13, v46, v104
	v_cmp_eq_u32_e64 s[0:1], 0, v114
	v_fmac_f32_e32 v55, v74, v106
	v_fmac_f32_e32 v53, v57, v100
	v_fmac_f32_e32 v52, v57, v97
	v_fmac_f32_e32 v44, v57, v99
	v_fmac_f32_e32 v47, v57, v95
	v_fmac_f32_e32 v36, v57, v103
	v_fmac_f32_e32 v37, v57, v104
	v_fmac_f32_e32 v38, v57, v106
	v_fmac_f32_e32 v41, v57, v96
	v_fmac_f32_e32 v34, v57, v92
	v_fmac_f32_e32 v32, v57, v93
	v_fmac_f32_e32 v31, v57, v94
	v_fmac_f32_e32 v33, v57, v108
	v_fmac_f32_e32 v29, v57, v98
	v_fmac_f32_e32 v28, v57, v101
	v_fmac_f32_e32 v27, v59, v101
	v_fmac_f32_e32 v25, v8, v100
	v_fmac_f32_e32 v24, v7, v100
	v_fmac_f32_e32 v23, v7, v97
	v_fmac_f32_e32 v26, v7, v99
	v_fmac_f32_e32 v21, v7, v95
	v_fmac_f32_e32 v20, v7, v103
	v_fmac_f32_e32 v19, v7, v104
	v_fmac_f32_e32 v22, v39, v99
	v_fmac_f32_e32 v17, v39, v95
	v_fmac_f32_e32 v16, v39, v103
	v_fmac_f32_e32 v15, v39, v104
	v_fmac_f32_e32 v18, v46, v95
	v_fmac_f32_e32 v14, v46, v103
	v_fmac_f32_e32 v13, v45, v103
	v_cndmask_b32_e64 v7, v54, v30, s[0:1]
	v_fmac_f32_e32 v55, v71, v104
	v_fmac_f32_e32 v52, v59, v100
	v_fmac_f32_e32 v44, v59, v97
	v_fmac_f32_e32 v47, v59, v99
	v_fmac_f32_e32 v36, v59, v95
	v_fmac_f32_e32 v37, v59, v103
	v_fmac_f32_e32 v38, v59, v104
	v_fmac_f32_e32 v41, v59, v106
	v_fmac_f32_e32 v34, v59, v96
	v_fmac_f32_e32 v32, v59, v92
	v_fmac_f32_e32 v31, v59, v93
	v_fmac_f32_e32 v33, v59, v94
	v_fmac_f32_e32 v29, v59, v108
	v_fmac_f32_e32 v28, v59, v98
	v_fmac_f32_e32 v27, v60, v98
	v_fmac_f32_e32 v22, v43, v97
	v_fmac_f32_e32 v17, v43, v99
	v_fmac_f32_e32 v16, v43, v95
	v_fmac_f32_e32 v15, v43, v103
	v_fmac_f32_e32 v18, v45, v99
	v_fmac_f32_e32 v14, v45, v95
	v_fmac_f32_e32 v13, v49, v95
	ds_bpermute_b32 v8, v186, v7
	v_cndmask_b32_e64 v7, v53, v25, s[0:1]
	v_fmac_f32_e32 v55, v69, v103
	v_fmac_f32_e32 v44, v60, v100
	v_fmac_f32_e32 v47, v60, v97
	v_fmac_f32_e32 v36, v60, v99
	v_fmac_f32_e32 v37, v60, v95
	v_fmac_f32_e32 v38, v60, v103
	v_fmac_f32_e32 v41, v60, v104
	v_fmac_f32_e32 v34, v60, v106
	v_fmac_f32_e32 v32, v60, v96
	v_fmac_f32_e32 v31, v60, v92
	v_fmac_f32_e32 v33, v60, v93
	v_fmac_f32_e32 v29, v60, v94
	v_fmac_f32_e32 v28, v60, v108
	v_fmac_f32_e32 v27, v62, v108
	v_fmac_f32_e32 v23, v35, v100
	v_fmac_f32_e32 v26, v35, v97
	v_fmac_f32_e32 v21, v35, v99
	v_fmac_f32_e32 v20, v35, v95
	v_fmac_f32_e32 v19, v35, v103
	v_fmac_f32_e32 v22, v42, v100
	v_fmac_f32_e32 v17, v42, v97
	v_fmac_f32_e32 v16, v42, v99
	v_fmac_f32_e32 v15, v42, v95
	v_fmac_f32_e32 v18, v49, v97
	v_fmac_f32_e32 v14, v49, v99
	v_fmac_f32_e32 v13, v48, v99
	ds_bpermute_b32 v42, v186, v7
	v_cndmask_b32_e64 v7, v52, v24, s[0:1]
	v_fmac_f32_e32 v55, v66, v95
	v_fmac_f32_e32 v47, v62, v100
	v_fmac_f32_e32 v36, v62, v97
	v_fmac_f32_e32 v37, v62, v99
	v_fmac_f32_e32 v38, v62, v95
	v_fmac_f32_e32 v41, v62, v103
	v_fmac_f32_e32 v34, v62, v104
	v_fmac_f32_e32 v32, v62, v106
	v_fmac_f32_e32 v31, v62, v96
	v_fmac_f32_e32 v33, v62, v92
	v_fmac_f32_e32 v29, v62, v93
	v_fmac_f32_e32 v28, v62, v94
	v_fmac_f32_e32 v27, v64, v94
	v_fmac_f32_e32 v26, v9, v100
	v_fmac_f32_e32 v21, v9, v97
	v_fmac_f32_e32 v20, v9, v99
	v_fmac_f32_e32 v19, v9, v95
	v_fmac_f32_e32 v18, v48, v100
	v_fmac_f32_e32 v14, v48, v97
	v_fmac_f32_e32 v13, v51, v97
	ds_bpermute_b32 v48, v186, v7
	v_cndmask_b32_e64 v7, v44, v23, s[0:1]
	v_fmac_f32_e32 v55, v63, v99
	v_fmac_f32_e32 v36, v64, v100
	v_fmac_f32_e32 v37, v64, v97
	v_fmac_f32_e32 v38, v64, v99
	v_fmac_f32_e32 v41, v64, v95
	v_fmac_f32_e32 v34, v64, v103
	v_fmac_f32_e32 v32, v64, v104
	v_fmac_f32_e32 v31, v64, v106
	v_fmac_f32_e32 v33, v64, v96
	v_fmac_f32_e32 v29, v64, v92
	v_fmac_f32_e32 v28, v64, v93
	v_fmac_f32_e32 v27, v65, v93
	v_fmac_f32_e32 v21, v40, v100
	v_fmac_f32_e32 v20, v40, v97
	v_fmac_f32_e32 v19, v40, v99
	v_fmac_f32_e32 v13, v50, v100
	ds_bpermute_b32 v50, v186, v7
	v_cndmask_b32_e64 v7, v47, v26, s[0:1]
	v_fmac_f32_e32 v55, v61, v97
	v_fmac_f32_e32 v37, v65, v100
	v_fmac_f32_e32 v38, v65, v97
	v_fmac_f32_e32 v41, v65, v99
	v_fmac_f32_e32 v34, v65, v95
	v_fmac_f32_e32 v32, v65, v103
	v_fmac_f32_e32 v31, v65, v104
	v_fmac_f32_e32 v33, v65, v106
	v_fmac_f32_e32 v29, v65, v96
	v_fmac_f32_e32 v28, v65, v92
	v_fmac_f32_e32 v27, v67, v92
	v_fmac_f32_e32 v20, v39, v100
	v_fmac_f32_e32 v19, v39, v97
	ds_bpermute_b32 v56, v186, v7
	v_cndmask_b32_e64 v7, v36, v21, s[0:1]
	v_fmac_f32_e32 v55, v58, v100
	v_fmac_f32_e32 v38, v67, v100
	v_fmac_f32_e32 v41, v67, v97
	v_fmac_f32_e32 v34, v67, v99
	v_fmac_f32_e32 v32, v67, v95
	v_fmac_f32_e32 v31, v67, v103
	v_fmac_f32_e32 v33, v67, v104
	v_fmac_f32_e32 v29, v67, v106
	v_fmac_f32_e32 v28, v67, v96
	v_fmac_f32_e32 v27, v68, v96
	v_fmac_f32_e32 v19, v43, v100
	ds_bpermute_b32 v58, v186, v7
	v_cndmask_b32_e64 v7, v37, v20, s[0:1]
	v_fmac_f32_e32 v41, v68, v100
; __device__ __forceinline__ float wave_reduce32(const float (&v)[32], int lane) {
;     float a[16], b[8], c[4], d[2], e;
;     { const bool h = lane & 32;
; #pragma unroll
;       for (int t = 0; t < 16; ++t) { const float keep = h ? v[t + 16] : v[t], send = h ? v[t] : v[t + 16]; a[t] = keep + __shfl_xor(send, 32); } }
;     { const bool h = lane & 16;
; #pragma unroll
;       for (int t = 0; t < 8; ++t) { const float keep = h ? a[t + 8] : a[t], send = h ? a[t] : a[t + 8]; b[t] = keep + __shfl_xor(send, 16); } }
;     { const bool h = lane & 8;
; #pragma unroll
;       for (int t = 0; t < 4; ++t) { const float keep = h ? b[t + 4] : b[t], send = h ? b[t] : b[t + 4]; c[t] = keep + __shfl_xor(send, 8); } }
; __device__ __forceinline__ void conv_tile(const Params& p, int l, int item, const bf16* PROJ, bf16* CV, LAS float* sl) {
;     ...
;         y[t] = acc; y2[t] = acc * acc; }
	v_fmac_f32_e32 v34, v68, v97
	v_fmac_f32_e32 v32, v68, v99
	v_fmac_f32_e32 v31, v68, v95
	v_fmac_f32_e32 v33, v68, v103
	v_fmac_f32_e32 v29, v68, v104
	v_fmac_f32_e32 v28, v68, v106
	v_fmac_f32_e32 v27, v70, v106
	ds_bpermute_b32 v60, v186, v7
	v_cndmask_b32_e64 v7, v38, v19, s[0:1]
	v_fmac_f32_e32 v34, v70, v100
	v_fmac_f32_e32 v32, v70, v97
	v_fmac_f32_e32 v31, v70, v99
	v_fmac_f32_e32 v33, v70, v95
	v_fmac_f32_e32 v29, v70, v103
	v_fmac_f32_e32 v28, v70, v104
	v_fmac_f32_e32 v27, v72, v104
	v_fmac_f32_e32 v17, v46, v100
	v_fmac_f32_e32 v16, v46, v97
	v_fmac_f32_e32 v15, v46, v99
	ds_bpermute_b32 v62, v186, v7
	v_cndmask_b32_e64 v7, v41, v22, s[0:1]
	v_fmac_f32_e32 v32, v72, v100
	v_fmac_f32_e32 v31, v72, v97
	v_fmac_f32_e32 v33, v72, v99
	v_fmac_f32_e32 v29, v72, v95
	v_fmac_f32_e32 v28, v72, v103
	v_fmac_f32_e32 v27, v73, v103
	v_fmac_f32_e32 v16, v45, v100
	v_fmac_f32_e32 v15, v45, v97
	ds_bpermute_b32 v64, v186, v7
	v_cndmask_b32_e64 v7, v34, v17, s[0:1]
	v_fmac_f32_e32 v31, v73, v100
	v_fmac_f32_e32 v33, v73, v97
	v_fmac_f32_e32 v29, v73, v99
	v_fmac_f32_e32 v28, v73, v95
	v_fmac_f32_e32 v27, v75, v95
	v_fmac_f32_e32 v15, v49, v100
	ds_bpermute_b32 v66, v186, v7
	v_cndmask_b32_e64 v7, v32, v16, s[0:1]
	v_fmac_f32_e32 v33, v75, v100
	v_fmac_f32_e32 v29, v75, v97
	v_fmac_f32_e32 v28, v75, v99
	v_fmac_f32_e32 v27, v115, v99
	ds_bpermute_b32 v68, v186, v7
	v_cndmask_b32_e64 v7, v31, v15, s[0:1]
	v_fmac_f32_e32 v29, v115, v100
	v_fmac_f32_e32 v28, v115, v97
	v_fmac_f32_e32 v27, v116, v97
	v_fmac_f32_e32 v14, v51, v100
	ds_bpermute_b32 v70, v186, v7
	v_cndmask_b32_e64 v7, v33, v18, s[0:1]
	v_fmac_f32_e32 v28, v116, v100
	v_fmac_f32_e32 v27, v117, v100
	ds_bpermute_b32 v72, v186, v7
	v_cndmask_b32_e64 v7, v29, v14, s[0:1]
	v_mul_f32_e32 v113, v55, v55
	v_mul_f32_e32 v119, v27, v27
	ds_bpermute_b32 v78, v186, v7
	v_cndmask_b32_e64 v7, v28, v13, s[0:1]
	v_mul_f32_e32 v127, v38, v38
	v_mul_f32_e32 v74, v19, v19
	v_cndmask_b32_e64 v6, v55, v27, s[0:1]
	ds_bpermute_b32 v82, v186, v7
	v_cndmask_b32_e64 v7, v113, v119, s[0:1]
	v_mul_f32_e32 v118, v54, v54
	v_mul_f32_e32 v134, v30, v30
	ds_bpermute_b32 v6, v186, v6
	ds_bpermute_b32 v7, v186, v7
	v_cndmask_b32_e64 v63, v127, v74, s[0:1]
	v_mul_f32_e32 v128, v41, v41
	v_mul_f32_e32 v135, v22, v22
	v_cndmask_b32_e64 v9, v118, v134, s[0:1]
	ds_bpermute_b32 v63, v186, v63
	v_mul_f32_e32 v120, v53, v53
	v_mul_f32_e32 v133, v29, v29
	v_mul_f32_e32 v111, v25, v25
	v_mul_f32_e32 v140, v14, v14
	ds_bpermute_b32 v9, v186, v9
	v_cndmask_b32_e64 v65, v128, v135, s[0:1]
	v_mul_f32_e32 v122, v52, v52
	v_mul_f32_e32 v126, v37, v37
	v_mul_f32_e32 v129, v34, v34
	v_mul_f32_e32 v121, v28, v28
	v_mul_f32_e32 v91, v24, v24
	v_mul_f32_e32 v76, v20, v20
	v_mul_f32_e32 v136, v17, v17
	v_mul_f32_e32 v35, v13, v13
	v_cndmask_b32_e64 v43, v120, v111, s[0:1]
	ds_bpermute_b32 v65, v186, v65
	v_cndmask_b32_e64 v75, v133, v140, s[0:1]
	v_mul_f32_e32 v123, v44, v44
	v_mul_f32_e32 v130, v32, v32
	v_mul_f32_e32 v90, v23, v23
	v_mul_f32_e32 v137, v16, v16
	ds_bpermute_b32 v43, v186, v43
	v_cndmask_b32_e64 v49, v122, v91, s[0:1]
	v_cndmask_b32_e64 v61, v126, v76, s[0:1]
	v_cndmask_b32_e64 v67, v129, v136, s[0:1]
	ds_bpermute_b32 v79, v186, v75
	v_cndmask_b32_e64 v75, v121, v35, s[0:1]
	v_cndmask_b32_e64 v84, v27, v55, s[0:1]
	v_cndmask_b32_e64 v85, v119, v113, s[0:1]
	v_mul_f32_e32 v131, v31, v31
	v_mul_f32_e32 v138, v15, v15
	ds_bpermute_b32 v49, v186, v49
	v_cndmask_b32_e64 v51, v123, v90, s[0:1]
	ds_bpermute_b32 v61, v186, v61
	ds_bpermute_b32 v67, v186, v67
	v_cndmask_b32_e64 v69, v130, v137, s[0:1]
	ds_bpermute_b32 v83, v186, v75
	s_waitcnt lgkmcnt(9)
	v_pk_add_f32 v[6:7], v[84:85], v[6:7]
	v_cndmask_b32_e64 v84, v19, v38, s[0:1]
	v_cndmask_b32_e64 v85, v74, v127, s[0:1]
	ds_bpermute_b32 v51, v186, v51
	ds_bpermute_b32 v69, v186, v69
	v_cndmask_b32_e64 v71, v131, v138, s[0:1]
	s_waitcnt lgkmcnt(10)
	v_pk_add_f32 v[62:63], v[84:85], v[62:63]
	v_cndmask_b32_e64 v84, v30, v54, s[0:1]
	v_cndmask_b32_e64 v85, v134, v118, s[0:1]
	v_and_b32_e32 v39, 16, v2
	ds_bpermute_b32 v71, v186, v71
	s_waitcnt lgkmcnt(10)
	v_pk_add_f32 v[8:9], v[84:85], v[8:9]
	v_cndmask_b32_e64 v84, v22, v41, s[0:1]
	v_cndmask_b32_e64 v85, v135, v128, s[0:1]
	v_mul_f32_e32 v125, v36, v36
	v_mul_f32_e32 v77, v21, v21
	v_cmp_eq_u32_e32 vcc, 0, v39
	s_waitcnt lgkmcnt(9)
	v_pk_add_f32 v[64:65], v[84:85], v[64:65]
	v_cndmask_b32_e64 v84, v25, v53, s[0:1]
	v_cndmask_b32_e64 v85, v111, v120, s[0:1]
	v_cndmask_b32_e64 v59, v125, v77, s[0:1]
	v_cndmask_b32_e32 v39, v6, v62, vcc
	s_waitcnt lgkmcnt(8)
	v_pk_add_f32 v[42:43], v[84:85], v[42:43]
	v_cndmask_b32_e64 v84, v17, v34, s[0:1]
	v_cndmask_b32_e64 v85, v136, v129, s[0:1]
	v_cndmask_b32_e64 v86, v24, v52, s[0:1]
	v_cndmask_b32_e64 v87, v91, v122, s[0:1]
	v_cndmask_b32_e64 v93, v77, v125, s[0:1]
	v_cndmask_b32_e64 v94, v20, v37, s[0:1]
	v_cndmask_b32_e64 v95, v76, v126, s[0:1]
	v_cndmask_b32_e64 v76, v13, v28, s[0:1]
	v_cndmask_b32_e64 v77, v35, v121, s[0:1]
	ds_bpermute_b32 v74, v187, v39
	v_cndmask_b32_e32 v39, v8, v64, vcc
	s_waitcnt lgkmcnt(5)
	v_pk_add_f32 v[66:67], v[84:85], v[66:67]
	v_pk_add_f32 v[48:49], v[86:87], v[48:49]
	v_cndmask_b32_e64 v86, v16, v32, s[0:1]
	v_cndmask_b32_e64 v87, v137, v130, s[0:1]
	v_cndmask_b32_e64 v88, v23, v44, s[0:1]
	v_cndmask_b32_e64 v89, v90, v123, s[0:1]
	v_pk_add_f32 v[60:61], v[94:95], v[60:61]
	s_waitcnt lgkmcnt(4)
	v_pk_add_f32 v[76:77], v[76:77], v[82:83]
	ds_bpermute_b32 v80, v187, v39
	v_cndmask_b32_e32 v39, v42, v66, vcc
	s_waitcnt lgkmcnt(3)
; __device__ __forceinline__ float wave_reduce32(const float (&v)[32], int lane) {
;     ...
;     { const bool h = lane & 16;
; #pragma unroll
;       for (int t = 0; t < 8; ++t) { const float keep = h ? a[t + 8] : a[t], send = h ? a[t] : a[t + 8]; b[t] = keep + __shfl_xor(send, 16); } }
;     { const bool h = lane & 8;
; #pragma unroll
;       for (int t = 0; t < 4; ++t) { const float keep = h ? b[t + 4] : b[t], send = h ? b[t] : b[t + 4]; c[t] = keep + __shfl_xor(send, 8); } }
;     { const bool h = lane & 4;
; #pragma unroll
;       for (int t = 0; t < 2; ++t) { const float keep = h ? c[t + 2] : c[t], send = h ? c[t] : c[t + 2]; d[t] = keep + __shfl_xor(send, 4); } }
;     { const bool h = lane & 2; const float keep = h ? d[1] : d[0], send = h ? d[0] : d[1]; e = keep + __shfl_xor(send, 2); }
;     e += __shfl_xor(e, 1);
;     return e;
; }
; __device__ __forceinline__ void conv_tile(const Params& p, int l, int item, const bf16* PROJ, bf16* CV, LAS float* sl) {
;     ...
;     const int tl = 16 * ((lane >> 5) & 1) + 8 * ((lane >> 4) & 1) + 4 * ((lane >> 3) & 1) + 2 * ((lane >> 2) & 1) + ((lane >> 1) & 1);
;     __syncthreads();
;     if ((lane & 1) == 0) { part[(tl * 8 + wave) * 2] = r1; part[(tl * 8 + wave) * 2 + 1] = r2; }
	v_pk_add_f32 v[68:69], v[86:87], v[68:69]
	v_pk_add_f32 v[50:51], v[88:89], v[50:51]
	v_cndmask_b32_e64 v88, v15, v31, s[0:1]
	v_cndmask_b32_e64 v89, v138, v131, s[0:1]
	v_cndmask_b32_e32 v35, v60, v76, vcc
	v_mul_f32_e32 v124, v47, v47
	v_mul_f32_e32 v81, v26, v26
	ds_bpermute_b32 v84, v187, v39
	v_cndmask_b32_e32 v39, v48, v68, vcc
	s_waitcnt lgkmcnt(3)
	v_pk_add_f32 v[70:71], v[88:89], v[70:71]
	ds_bpermute_b32 v82, v187, v35
	v_cndmask_b32_e32 v35, v7, v63, vcc
	v_cndmask_b32_e64 v57, v124, v81, s[0:1]
	ds_bpermute_b32 v86, v187, v39
	v_cndmask_b32_e32 v39, v50, v70, vcc
	ds_bpermute_b32 v75, v187, v35
	v_cndmask_b32_e32 v35, v51, v71, vcc
	v_mul_f32_e32 v132, v33, v33
	v_mul_f32_e32 v139, v18, v18
	ds_bpermute_b32 v57, v186, v57
	ds_bpermute_b32 v59, v186, v59
	ds_bpermute_b32 v88, v187, v39
	ds_bpermute_b32 v89, v187, v35
	v_cndmask_b32_e64 v73, v132, v139, s[0:1]
	ds_bpermute_b32 v73, v186, v73
	v_and_b32_e32 v40, 8, v2
	v_cndmask_b32_e64 v90, v26, v47, s[0:1]
	v_cndmask_b32_e64 v91, v81, v124, s[0:1]
	v_cndmask_b32_e64 v92, v21, v36, s[0:1]
	v_cndmask_b32_e32 v7, v63, v7, vcc
	v_cndmask_b32_e32 v6, v62, v6, vcc
	v_cndmask_b32_e32 v51, v71, v51, vcc
	v_cndmask_b32_e32 v50, v70, v50, vcc
	s_waitcnt lgkmcnt(4)
	v_pk_add_f32 v[56:57], v[90:91], v[56:57]
	v_cndmask_b32_e64 v90, v18, v33, s[0:1]
	v_cndmask_b32_e64 v91, v139, v132, s[0:1]
	s_waitcnt lgkmcnt(3)
	v_pk_add_f32 v[58:59], v[92:93], v[58:59]
	v_cndmask_b32_e64 v92, v14, v29, s[0:1]
	v_cndmask_b32_e64 v93, v140, v133, s[0:1]
	v_pk_add_f32 v[6:7], v[6:7], v[74:75]
	s_waitcnt lgkmcnt(1)
	v_pk_add_f32 v[50:51], v[50:51], v[88:89]
	v_cmp_eq_u32_e64 s[0:1], 0, v40
	s_waitcnt lgkmcnt(0)
	v_pk_add_f32 v[72:73], v[90:91], v[72:73]
	v_cndmask_b32_e32 v8, v64, v8, vcc
	v_cndmask_b32_e64 v35, v6, v50, s[0:1]
	ds_bpermute_b32 v62, v180, v35
	v_cndmask_b32_e32 v35, v9, v65, vcc
	v_cndmask_b32_e32 v39, v56, v72, vcc
	ds_bpermute_b32 v81, v187, v35
	v_cndmask_b32_e32 v35, v57, v73, vcc
	ds_bpermute_b32 v90, v187, v39
	ds_bpermute_b32 v91, v187, v35
	v_cndmask_b32_e32 v9, v65, v9, vcc
	v_cndmask_b32_e32 v57, v73, v57, vcc
	v_cndmask_b32_e32 v56, v72, v56, vcc
	s_waitcnt lgkmcnt(2)
	v_pk_add_f32 v[8:9], v[8:9], v[80:81]
	s_waitcnt lgkmcnt(0)
	v_pk_add_f32 v[56:57], v[56:57], v[90:91]
	v_pk_add_f32 v[78:79], v[92:93], v[78:79]
	v_cndmask_b32_e64 v35, v8, v56, s[0:1]
	ds_bpermute_b32 v64, v180, v35
	v_cndmask_b32_e32 v35, v43, v67, vcc
	v_cndmask_b32_e32 v39, v58, v78, vcc
	ds_bpermute_b32 v85, v187, v35
	v_cndmask_b32_e32 v35, v59, v79, vcc
	ds_bpermute_b32 v92, v187, v39
	ds_bpermute_b32 v93, v187, v35
	v_cndmask_b32_e32 v43, v67, v43, vcc
	v_cndmask_b32_e32 v42, v66, v42, vcc
	v_cndmask_b32_e32 v59, v79, v59, vcc
	v_cndmask_b32_e32 v58, v78, v58, vcc
	s_waitcnt lgkmcnt(2)
	v_pk_add_f32 v[42:43], v[42:43], v[84:85]
	s_waitcnt lgkmcnt(0)
	v_pk_add_f32 v[58:59], v[58:59], v[92:93]
	v_cndmask_b32_e32 v48, v68, v48, vcc
	v_cndmask_b32_e64 v35, v42, v58, s[0:1]
	ds_bpermute_b32 v66, v180, v35
	v_cndmask_b32_e32 v35, v49, v69, vcc
	ds_bpermute_b32 v87, v187, v35
	v_cndmask_b32_e32 v35, v61, v77, vcc
	ds_bpermute_b32 v83, v187, v35
	v_cndmask_b32_e32 v49, v69, v49, vcc
	v_cndmask_b32_e32 v61, v77, v61, vcc
	v_cndmask_b32_e32 v60, v76, v60, vcc
	s_waitcnt lgkmcnt(1)
	v_pk_add_f32 v[48:49], v[48:49], v[86:87]
	s_waitcnt lgkmcnt(0)
	v_pk_add_f32 v[60:61], v[60:61], v[82:83]
	v_and_b32_e32 v45, 4, v2
	v_cndmask_b32_e64 v35, v48, v60, s[0:1]
	ds_bpermute_b32 v68, v180, v35
	v_cndmask_b32_e64 v35, v7, v51, s[0:1]
	ds_bpermute_b32 v63, v180, v35
	v_cndmask_b32_e64 v35, v43, v59, s[0:1]
	ds_bpermute_b32 v67, v180, v35
	v_cndmask_b32_e64 v7, v51, v7, s[0:1]
	v_cndmask_b32_e64 v6, v50, v6, s[0:1]
	v_cndmask_b32_e64 v43, v59, v43, s[0:1]
	v_cndmask_b32_e64 v42, v58, v42, s[0:1]
	s_waitcnt lgkmcnt(1)
	v_pk_add_f32 v[6:7], v[6:7], v[62:63]
	s_waitcnt lgkmcnt(0)
	v_pk_add_f32 v[42:43], v[42:43], v[66:67]
	v_cmp_eq_u32_e32 vcc, 0, v45
	v_cndmask_b32_e64 v8, v56, v8, s[0:1]
	v_cndmask_b32_e64 v48, v60, v48, s[0:1]
	v_cndmask_b32_e32 v35, v6, v42, vcc
	ds_bpermute_b32 v50, v179, v35
	v_cndmask_b32_e64 v35, v9, v57, s[0:1]
	ds_bpermute_b32 v65, v180, v35
	v_cndmask_b32_e64 v35, v49, v61, s[0:1]
	ds_bpermute_b32 v69, v180, v35
	v_cndmask_b32_e64 v9, v57, v9, s[0:1]
	v_cndmask_b32_e64 v49, v61, v49, s[0:1]
	s_waitcnt lgkmcnt(1)
	v_pk_add_f32 v[8:9], v[8:9], v[64:65]
	v_and_b32_e32 v46, 2, v2
	s_waitcnt lgkmcnt(0)
	v_pk_add_f32 v[48:49], v[48:49], v[68:69]
	v_cndmask_b32_e32 v6, v42, v6, vcc
	v_cndmask_b32_e32 v35, v8, v48, vcc
	ds_bpermute_b32 v56, v179, v35
	v_cndmask_b32_e32 v35, v7, v43, vcc
	ds_bpermute_b32 v51, v179, v35
	v_cndmask_b32_e32 v35, v9, v49, vcc
	ds_bpermute_b32 v57, v179, v35
	v_cndmask_b32_e32 v7, v43, v7, vcc
	v_cndmask_b32_e32 v9, v49, v9, vcc
	v_cndmask_b32_e32 v8, v48, v8, vcc
	s_waitcnt lgkmcnt(1)
	v_pk_add_f32 v[6:7], v[6:7], v[50:51]
	s_waitcnt lgkmcnt(0)
	v_pk_add_f32 v[8:9], v[8:9], v[56:57]
	v_cmp_eq_u32_e32 vcc, 0, v46
	v_readfirstlane_b32 s9, v2
	v_readlane_b32 s81, v251, 34
	v_cndmask_b32_e32 v35, v6, v8, vcc
	ds_bpermute_b32 v42, v178, v35
	v_cndmask_b32_e32 v35, v7, v9, vcc
	ds_bpermute_b32 v43, v178, v35
	v_cndmask_b32_e32 v7, v9, v7, vcc
	v_cndmask_b32_e32 v6, v8, v6, vcc
	v_and_b32_e32 v35, 1, v2
	v_cmp_eq_u32_e32 vcc, 0, v35
	s_waitcnt lgkmcnt(0)
	v_pk_add_f32 v[6:7], v[6:7], v[42:43]
	ds_bpermute_b32 v8, v162, v6
	ds_bpermute_b32 v9, v162, v7
	v_readlane_b32 s82, v251, 35
	v_readlane_b32 s83, v251, 36
	v_readlane_b32 s86, v251, 39
	v_readlane_b32 s87, v251, 40
	v_readlane_b32 s88, v251, 41
	v_readlane_b32 s89, v251, 42
	v_readlane_b32 s90, v251, 43
	v_readlane_b32 s91, v251, 44
	v_readlane_b32 s92, v251, 45
	v_readlane_b32 s93, v251, 46
	v_readlane_b32 s94, v251, 47
	v_readlane_b32 s95, v251, 48
	s_waitcnt lgkmcnt(0)
	s_barrier
	s_and_saveexec_b64 s[0:1], vcc
	s_cbranch_execz .LBB0_347
	s_ashr_i32 s9, s9, 5
	s_lshl_b32 s9, s9, 2
	v_lshlrev_b32_e32 v35, 5, v2
	s_and_b32 s9, s9, -8
	v_and_b32_e32 v35, 0x7c0, v35
	s_add_i32 s9, s9, 0
	v_add_u32_e32 v35, s9, v35
	v_add_u32_e32 v35, 0x20000, v35
	v_pk_add_f32 v[6:7], v[6:7], v[8:9]
	ds_write_b64 v35, v[6:7]
